# wave_sum butterflies (ds_bpermute x6) in the rmsnorm phases replaced by DPP row reductions plus readlane broadcast
# baseline (speedup 1.0000x reference)
; __device__ __forceinline__ float wave_sum(float v) {
; #pragma unroll
;     for (int o = 1; o < 64; o <<= 1) v += __shfl_xor(v, o);
;     return v;
; }
; __device__ __forceinline__ void norm1_row(const Params& p, const f32x4 (&v)[8], const f32x4 (&sc)[8], const f32x4 (&sh)[8], int row, int lane) {
;     bf16_t* H = (bf16_t*)(p.ws + WS_H);
;     float ss = 0.f;
; #pragma unroll
;     for (int j = 0; j < 8; ++j) ss += (v[j].x * v[j].x + v[j].y * v[j].y) + (v[j].z * v[j].z + v[j].w * v[j].w);
;     const float rstd = 1.0f / sqrtf(wave_sum(ss) * (1.0f / DM) + EPS);
.LBB0_168:
	s_or_b64 exec, exec, s[0:1]
	s_waitcnt vmcnt(23)
	v_mov_b32_e32 v160, v61
	s_waitcnt vmcnt(22)
	v_mov_b32_e32 v161, v57
	v_mov_b32_e32 v158, v60
	v_mov_b32_e32 v159, v56
	v_pk_mul_f32 v[160:161], v[160:161], v[160:161]
	v_mov_b32_e32 v162, v63
	v_mov_b32_e32 v163, v59
	v_pk_fma_f32 v[158:159], v[158:159], v[158:159], v[160:161]
	v_mov_b32_e32 v160, v62
	v_mov_b32_e32 v161, v58
	v_pk_mul_f32 v[162:163], v[162:163], v[162:163]
	s_waitcnt vmcnt(19)
	v_mul_f32_e32 v135, v12, v12
	v_pk_fma_f32 v[160:161], v[160:161], v[160:161], v[162:163]
	v_pk_mul_f32 v[162:163], v[52:53], v[52:53]
	v_pk_add_f32 v[158:159], v[158:159], v[160:161]
	v_pk_mul_f32 v[160:161], v[54:55], v[54:55]
	v_mul_f32_e32 v137, v13, v13
	v_pk_mov_b32 v[164:165], v[162:163], v[160:161] op_sel:[1,0]
	v_mov_b32_e32 v163, v161
	v_pk_add_f32 v[160:161], v[164:165], v[162:163]
	v_pk_add_f32 v[158:159], v[158:159], v[158:159] op_sel:[0,1] op_sel_hi:[1,0]
	v_pk_add_f32 v[160:161], v[160:161], v[160:161] op_sel:[0,1] op_sel_hi:[1,0]
	v_mov_b32_e32 v159, v135
	v_mov_b32_e32 v161, v137
	v_pk_add_f32 v[158:159], v[158:159], v[160:161]
	v_mul_f32_e32 v160, v33, v33
	v_mul_f32_e32 v162, v35, v35
	v_mul_f32_e32 v139, v14, v14
	v_mul_f32_e32 v141, v15, v15
	v_pk_fma_f32 v[160:161], v[32:33], v[32:33], v[160:161] op_sel_hi:[1,1,0]
	v_pk_fma_f32 v[162:163], v[34:35], v[34:35], v[162:163] op_sel_hi:[1,1,0]
	v_mov_b32_e32 v161, v139
	v_mov_b32_e32 v163, v141
	v_pk_add_f32 v[160:161], v[160:161], v[162:163]
	s_waitcnt vmcnt(18)
	v_pk_mul_f32 v[162:163], v[8:9], v[8:9]
	v_pk_add_f32 v[158:159], v[158:159], v[160:161]
	v_pk_mul_f32 v[160:161], v[10:11], v[10:11]
	s_waitcnt vmcnt(16)
	v_mul_f32_e32 v135, v0, v0
	v_pk_mov_b32 v[164:165], v[162:163], v[160:161] op_sel:[1,0]
	v_mov_b32_e32 v163, v161
	v_pk_add_f32 v[160:161], v[164:165], v[162:163]
	v_mul_f32_e32 v137, v1, v1
	v_pk_add_f32 v[158:159], v[158:159], v[158:159] op_sel:[0,1] op_sel_hi:[1,0]
	v_pk_add_f32 v[160:161], v[160:161], v[160:161] op_sel:[0,1] op_sel_hi:[1,0]
	v_mov_b32_e32 v159, v135
	v_mov_b32_e32 v161, v137
	v_pk_add_f32 v[158:159], v[158:159], v[160:161]
	v_mul_f32_e32 v160, v5, v5
	v_mul_f32_e32 v162, v7, v7
	v_mul_f32_e32 v139, v2, v2
	v_mul_f32_e32 v141, v3, v3
	v_pk_fma_f32 v[160:161], v[4:5], v[4:5], v[160:161] op_sel_hi:[1,1,0]
	v_pk_fma_f32 v[162:163], v[6:7], v[6:7], v[162:163] op_sel_hi:[1,1,0]
	v_mov_b32_e32 v161, v139
	v_mov_b32_e32 v163, v141
	v_pk_add_f32 v[160:161], v[160:161], v[162:163]
	s_nop 0
	v_pk_add_f32 v[158:159], v[158:159], v[160:161]
	s_nop 0
	v_add_f32_e32 v135, v158, v159
	s_nop 1
	v_add_f32_dpp v135, v135, v135 quad_perm:[1,0,3,2] row_mask:0xf bank_mask:0xf
	s_nop 1
	v_add_f32_dpp v135, v135, v135 quad_perm:[2,3,0,1] row_mask:0xf bank_mask:0xf
	s_nop 1
	v_add_f32_dpp v135, v135, v135 row_half_mirror row_mask:0xf bank_mask:0xf
	s_nop 1
	v_add_f32_dpp v135, v135, v135 row_mirror row_mask:0xf bank_mask:0xf
	s_nop 1
	v_add_f32_dpp v135, v135, v135 row_bcast:15 row_mask:0xa bank_mask:0xf
	s_nop 1
	v_add_f32_dpp v135, v135, v135 row_bcast:31 row_mask:0xc bank_mask:0xf
	s_nop 1
	v_readlane_b32 s98, v135, 63
	s_waitcnt lgkmcnt(0)
	s_waitcnt lgkmcnt(0)
	s_waitcnt lgkmcnt(0)
	s_waitcnt lgkmcnt(0)
	s_waitcnt lgkmcnt(0)
	s_waitcnt lgkmcnt(0)
; __device__ __forceinline__ unsigned pk2(float lo, float hi) { unsigned r; asm("v_cvt_pk_bf16_f32 %0, %1, %2" : "=v"(r) : "v"(lo), "v"(hi)); return r; }
; __device__ __forceinline__ void norm1_row(const Params& p, const f32x4 (&v)[8], const f32x4 (&sc)[8], const f32x4 (&sh)[8], int row, int lane) {
;     ...
;     const float rstd = 1.0f / sqrtf(wave_sum(ss) * (1.0f / DM) + EPS);
; #pragma unroll
;     for (int j = 0; j < 8; ++j) { const int col = 4 * lane + 256 * j;
;         const f32x4 h = v[j] * rstd * sc[j] + sh[j];
;         u32x2 w; w.x = pk2(h.x, h.y); w.y = pk2(h.z, h.w);
;         *(u32x2*)(H + (size_t)row * DM + col) = w; }
; __device__ __forceinline__ void phase_norm1(const Params& p) {
;     ...
;         if (row + NGW < MPROMPT) { const f32x4* xr = (const f32x4*)(p.in[I_XP] + (size_t)(row + NGW) * DM) + lane;
; #pragma unroll
;             for (int j = 0; j < 8; ++j) vn[j] = __builtin_nontemporal_load(xr + 64 * j); }
;         norm1_row(p, v, sc, sh, row, lane);
; #pragma unroll
;         for (int j = 0; j < 8; ++j) v[j] = vn[j];
	s_nop 1
	v_mov_b32_e32 v135, s98
	v_fmamk_f32 v135, v135, 0x3a000000, v156
	v_mul_f32_e32 v137, 0x4f800000, v135
	v_cmp_gt_f32_e32 vcc, s17, v135
	s_nop 1
	v_cndmask_b32_e32 v135, v135, v137, vcc
	v_sqrt_f32_e32 v137, v135
	s_nop 0
	v_add_u32_e32 v139, -1, v137
	v_fma_f32 v141, -v139, v137, v135
	v_cmp_ge_f32_e64 s[6:7], 0, v141
	v_add_u32_e32 v141, 1, v137
	s_nop 0
	v_cndmask_b32_e64 v139, v137, v139, s[6:7]
	v_fma_f32 v137, -v141, v137, v135
	v_cmp_lt_f32_e64 s[6:7], 0, v137
	s_nop 1
	v_cndmask_b32_e64 v137, v139, v141, s[6:7]
	v_mul_f32_e32 v139, 0x37800000, v137
	v_cndmask_b32_e32 v137, v137, v139, vcc
	v_cmp_class_f32_e32 vcc, v135, v157
	s_nop 1
	v_cndmask_b32_e32 v135, v137, v135, vcc
	v_div_scale_f32 v137, s[0:1], v135, v135, 1.0
	v_rcp_f32_e32 v139, v137
	s_and_b64 s[0:1], exec, s[4:5]
	s_or_b64 s[12:13], s[0:1], s[12:13]
	v_fma_f32 v141, -v137, v139, 1.0
	v_fmac_f32_e32 v139, v141, v139
	v_div_scale_f32 v141, vcc, 1.0, v135, 1.0
	v_mul_f32_e32 v143, v141, v139
	v_fma_f32 v145, -v137, v143, v141
	v_fmac_f32_e32 v143, v145, v139
	v_fma_f32 v137, -v137, v143, v141
	v_div_fmas_f32 v137, v137, v139, v143
	v_div_fixup_f32 v158, v137, v135, 1.0
	v_pk_mul_f32 v[60:61], v[60:61], v[158:159] op_sel_hi:[1,0]
	v_pk_mul_f32 v[56:57], v[56:57], v[158:159] op_sel_hi:[1,0]
	v_pk_mul_f32 v[52:53], v[52:53], v[158:159] op_sel_hi:[1,0]
	v_pk_mul_f32 v[32:33], v[32:33], v[158:159] op_sel_hi:[1,0]
	v_pk_mul_f32 v[12:13], v[12:13], v[158:159] op_sel_hi:[1,0]
	v_pk_mul_f32 v[8:9], v[8:9], v[158:159] op_sel_hi:[1,0]
	v_pk_mul_f32 v[4:5], v[4:5], v[158:159] op_sel_hi:[1,0]
	v_pk_mul_f32 v[0:1], v[0:1], v[158:159] op_sel_hi:[1,0]
	v_pk_mul_f32 v[62:63], v[62:63], v[158:159] op_sel_hi:[1,0]
	s_waitcnt vmcnt(14)
	v_pk_fma_f32 v[60:61], v[116:117], v[60:61], v[120:121]
	v_pk_mul_f32 v[58:59], v[58:59], v[158:159] op_sel_hi:[1,0]
	s_waitcnt vmcnt(9)
	v_pk_fma_f32 v[56:57], v[124:125], v[56:57], v[112:113]
	v_pk_mul_f32 v[54:55], v[54:55], v[158:159] op_sel_hi:[1,0]
	v_pk_fma_f32 v[52:53], v[108:109], v[52:53], v[104:105]
	v_pk_mul_f32 v[34:35], v[34:35], v[158:159] op_sel_hi:[1,0]
	s_waitcnt vmcnt(8)
	v_pk_fma_f32 v[32:33], v[96:97], v[32:33], v[100:101]
	v_pk_mul_f32 v[14:15], v[14:15], v[158:159] op_sel_hi:[1,0]
	s_waitcnt vmcnt(6)
	v_pk_fma_f32 v[12:13], v[88:89], v[12:13], v[92:93]
	v_pk_mul_f32 v[10:11], v[10:11], v[158:159] op_sel_hi:[1,0]
	s_waitcnt vmcnt(4)
	v_pk_fma_f32 v[8:9], v[80:81], v[8:9], v[84:85]
	v_pk_mul_f32 v[6:7], v[6:7], v[158:159] op_sel_hi:[1,0]
	s_waitcnt vmcnt(2)
	v_pk_fma_f32 v[4:5], v[72:73], v[4:5], v[76:77]
	v_pk_mul_f32 v[2:3], v[2:3], v[158:159] op_sel_hi:[1,0]
	s_waitcnt vmcnt(0)
	v_pk_fma_f32 v[0:1], v[64:65], v[0:1], v[68:69]
	v_pk_fma_f32 v[62:63], v[118:119], v[62:63], v[122:123]
	v_cvt_pk_bf16_f32 v60, v60, v61
	v_pk_fma_f32 v[58:59], v[126:127], v[58:59], v[114:115]
	v_cvt_pk_bf16_f32 v61, v62, v63
	v_cvt_pk_bf16_f32 v56, v56, v57
	v_pk_fma_f32 v[54:55], v[110:111], v[54:55], v[106:107]
	v_cvt_pk_bf16_f32 v57, v58, v59
	v_cvt_pk_bf16_f32 v52, v52, v53
	v_pk_fma_f32 v[34:35], v[98:99], v[34:35], v[102:103]
	v_cvt_pk_bf16_f32 v53, v54, v55
	v_cvt_pk_bf16_f32 v32, v32, v33
	v_pk_fma_f32 v[14:15], v[90:91], v[14:15], v[94:95]
	v_cvt_pk_bf16_f32 v33, v34, v35
	v_cvt_pk_bf16_f32 v12, v12, v13
	v_pk_fma_f32 v[10:11], v[82:83], v[10:11], v[86:87]
	v_cvt_pk_bf16_f32 v13, v14, v15
	v_cvt_pk_bf16_f32 v8, v8, v9
	v_pk_fma_f32 v[6:7], v[74:75], v[6:7], v[78:79]
	v_cvt_pk_bf16_f32 v9, v10, v11
	v_cvt_pk_bf16_f32 v4, v4, v5
	v_pk_fma_f32 v[2:3], v[66:67], v[2:3], v[70:71]
	v_cvt_pk_bf16_f32 v5, v6, v7
	v_cvt_pk_bf16_f32 v0, v0, v1
	global_store_dwordx2 v[132:133], v[60:61], off
	v_cvt_pk_bf16_f32 v1, v2, v3
	global_store_dwordx2 v[132:133], v[56:57], off offset:512
	global_store_dwordx2 v[132:133], v[52:53], off offset:1024
	global_store_dwordx2 v[132:133], v[32:33], off offset:1536
	global_store_dwordx2 v[132:133], v[12:13], off offset:2048
	global_store_dwordx2 v[132:133], v[8:9], off offset:2560
	global_store_dwordx2 v[132:133], v[4:5], off offset:3072
	global_store_dwordx2 v[132:133], v[0:1], off offset:3584
	v_mov_b64_e32 v[62:63], v[18:19]
	v_mov_b64_e32 v[58:59], v[22:23]
	v_mov_b64_e32 v[54:55], v[26:27]
	v_mov_b64_e32 v[34:35], v[30:31]
	v_mov_b64_e32 v[12:13], v[36:37]
	v_mov_b64_e32 v[8:9], v[40:41]
	v_mov_b64_e32 v[4:5], v[44:45]
	v_mov_b64_e32 v[0:1], v[48:49]
	v_lshl_add_u64 v[132:133], v[132:133], 0, s[10:11]
	v_mov_b64_e32 v[60:61], v[16:17]
	v_mov_b64_e32 v[56:57], v[20:21]
	v_mov_b64_e32 v[52:53], v[24:25]
	v_mov_b64_e32 v[32:33], v[28:29]
	v_mov_b64_e32 v[14:15], v[38:39]
	v_mov_b64_e32 v[10:11], v[42:43]
	v_mov_b64_e32 v[6:7], v[46:47]
	v_mov_b64_e32 v[2:3], v[50:51]
	s_andn2_b64 exec, exec, s[12:13]
	s_cbranch_execz .LBB0_171

; __device__ __forceinline__ void norm1_row(const Params& p, const f32x4 (&v)[8], const f32x4 (&sc)[8], const f32x4 (&sh)[8], int row, int lane) {
;     bf16_t* H = (bf16_t*)(p.ws + WS_H);
;     float ss = 0.f;
; #pragma unroll
;     for (int j = 0; j < 8; ++j) ss += (v[j].x * v[j].x + v[j].y * v[j].y) + (v[j].z * v[j].z + v[j].w * v[j].w);
; __device__ __forceinline__ void phase_norm1(const Params& p) {
;     ...
;     for (int row = MPROMPT + (gw >> 1); (gw & 1) == 0 && row < MTOK; row += (NGW >> 1)) {
;         const float* ar = ada + (size_t)seq_of_row(row) * NADA; const f32x4* xr = (const f32x4*)xrow_ptr(p, row) + lane;
;         f32x4 x[8], sc[8], sh[8];
; #pragma unroll
;         for (int j = 0; j < 8; ++j) { const int col = 4 * lane + 256 * j; x[j] = __builtin_nontemporal_load(xr + 64 * j); sc[j] = *(const f32x4*)(ar + DM + col); sh[j] = *(const f32x4*)(ar + col); }
;         norm1_row(p, x, sc, sh, row, lane);
;     }
.LBB0_173:
	v_add_u32_e32 v24, 0x2000, v40
	v_lshrrev_b32_e32 v25, 3, v40
	v_ashrrev_i32_e32 v26, 11, v24
	v_add_u32_e32 v25, 4, v25
	v_cmp_gt_i32_e32 vcc, s1, v24
	s_nop 1
	v_cndmask_b32_e32 v41, v25, v26, vcc
	v_cndmask_b32_e32 v25, 0, v5, vcc
	v_cndmask_b32_e32 v24, v40, v4, vcc
	v_cndmask_b32_e32 v27, v34, v35, vcc
	v_cndmask_b32_e32 v26, v36, v37, vcc
	v_add_u32_e32 v40, s0, v40
	v_lshlrev_b64 v[24:25], 13, v[24:25]
	v_mad_i64_i32 v[42:43], s[4:5], v41, s3, v[6:7]
	v_add_u32_e32 v41, 0x2000, v40
	v_lshl_add_u64 v[24:25], v[26:27], 0, v[24:25]
	v_lshl_add_u64 v[46:47], v[42:43], 0, s[12:13]
	v_cmp_lt_i32_e32 vcc, s18, v41
	v_lshl_add_u64 v[86:87], v[24:25], 0, v[0:1]
	v_lshl_add_u64 v[82:83], v[42:43], 0, v[8:9]
	v_lshl_add_u64 v[48:49], v[46:47], 0, v[8:9]
	v_lshl_add_u64 v[78:79], v[46:47], 0, v[10:11]
	v_lshl_add_u64 v[70:71], v[46:47], 0, v[12:13]
	v_lshl_add_u64 v[74:75], v[46:47], 0, v[14:15]
	s_or_b64 s[14:15], vcc, s[14:15]
	v_add_co_u32_e32 v130, vcc, s16, v86
	v_lshl_add_u64 v[90:91], v[42:43], 0, v[16:17]
	v_lshl_add_u64 v[98:99], v[42:43], 0, v[18:19]
	v_lshl_add_u64 v[106:107], v[42:43], 0, v[20:21]
	v_lshl_add_u64 v[114:115], v[42:43], 0, v[22:23]
	global_load_dwordx4 v[24:27], v[82:83], off offset:1024
	global_load_dwordx4 v[42:45], v[82:83], off offset:2048
	v_lshl_add_u64 v[88:89], v[46:47], 0, v[16:17]
	v_lshl_add_u64 v[94:95], v[46:47], 0, v[18:19]
	v_lshl_add_u64 v[102:103], v[46:47], 0, v[20:21]
	v_lshl_add_u64 v[110:111], v[46:47], 0, v[22:23]
	global_load_dwordx4 v[46:49], v[48:49], off
	s_nop 0
	global_load_dwordx4 v[50:53], v[82:83], off
	global_load_dwordx4 v[54:57], v[86:87], off nt
	global_load_dwordx4 v[58:61], v[86:87], off offset:1024 nt
	global_load_dwordx4 v[62:65], v[86:87], off offset:2048 nt
	global_load_dwordx4 v[66:69], v[86:87], off offset:3072 nt
	s_nop 0
	global_load_dwordx4 v[70:73], v[70:71], off
	s_nop 0
	global_load_dwordx4 v[74:77], v[74:75], off
	s_nop 0
	global_load_dwordx4 v[78:81], v[78:79], off
	s_nop 0
	global_load_dwordx4 v[82:85], v[82:83], off offset:3072
	v_addc_co_u32_e32 v131, vcc, 0, v87, vcc
	global_load_dwordx4 v[86:89], v[88:89], off
	s_nop 0
	global_load_dwordx4 v[90:93], v[90:91], off
	s_nop 0
	global_load_dwordx4 v[94:97], v[94:95], off
	s_nop 0
	global_load_dwordx4 v[98:101], v[98:99], off
	s_nop 0
	global_load_dwordx4 v[102:105], v[102:103], off
	s_nop 0
	global_load_dwordx4 v[106:109], v[106:107], off
	s_nop 0
	global_load_dwordx4 v[110:113], v[110:111], off
	s_nop 0
	global_load_dwordx4 v[114:117], v[114:115], off
	s_nop 0
	global_load_dwordx4 v[118:121], v[130:131], off nt
	global_load_dwordx4 v[122:125], v[130:131], off offset:1024 nt
	global_load_dwordx4 v[126:129], v[130:131], off offset:3072 nt
	s_nop 0
	global_load_dwordx4 v[130:133], v[130:131], off offset:2048 nt
	v_lshl_add_u64 v[4:5], v[4:5], 0, s[8:9]
	s_waitcnt vmcnt(19)
	v_mov_b32_e32 v136, v55
	s_waitcnt vmcnt(18)
	v_mov_b32_e32 v137, v59
	v_mov_b32_e32 v140, v57
	v_mov_b32_e32 v141, v61
	v_mov_b32_e32 v134, v54
	v_mov_b32_e32 v135, v58
	v_mov_b32_e32 v138, v56
	v_mov_b32_e32 v139, v60
	s_waitcnt vmcnt(17)
	v_pk_mul_f32 v[142:143], v[64:65], v[64:65]
	v_pk_mul_f32 v[144:145], v[62:63], v[62:63]
	v_pk_mul_f32 v[136:137], v[136:137], v[136:137]
	v_pk_mul_f32 v[140:141], v[140:141], v[140:141]
	v_pk_mov_b32 v[150:151], v[144:145], v[142:143] op_sel:[1,0]
	v_mov_b32_e32 v145, v143
	v_pk_fma_f32 v[134:135], v[134:135], v[134:135], v[136:137]
	v_pk_fma_f32 v[136:137], v[138:139], v[138:139], v[140:141]
	s_waitcnt vmcnt(16)
	v_mul_f32_e32 v146, v67, v67
	v_mul_f32_e32 v148, v69, v69
	v_pk_add_f32 v[138:139], v[150:151], v[144:145]
	v_pk_add_f32 v[134:135], v[134:135], v[136:137]
	s_waitcnt vmcnt(3)
	v_mul_f32_e32 v41, v118, v118
	v_mul_f32_e32 v155, v119, v119
	v_mul_f32_e32 v157, v120, v120
	v_mul_f32_e32 v158, v121, v121
	v_pk_fma_f32 v[142:143], v[66:67], v[66:67], v[146:147] op_sel_hi:[1,1,0]
	v_pk_fma_f32 v[146:147], v[68:69], v[68:69], v[148:149] op_sel_hi:[1,1,0]
	v_pk_add_f32 v[136:137], v[138:139], v[138:139] op_sel:[0,1] op_sel_hi:[1,0]
	v_pk_add_f32 v[134:135], v[134:135], v[134:135] op_sel:[0,1] op_sel_hi:[1,0]
	s_waitcnt vmcnt(2)
	v_pk_mul_f32 v[148:149], v[124:125], v[124:125]
	v_pk_mul_f32 v[152:153], v[122:123], v[122:123]
	v_mov_b32_e32 v143, v157
	v_mov_b32_e32 v147, v158
	v_mov_b32_e32 v137, v155
	v_mov_b32_e32 v135, v41
	v_pk_mov_b32 v[140:141], v[152:153], v[148:149] op_sel:[1,0]
	v_mov_b32_e32 v153, v149
	v_pk_add_f32 v[138:139], v[142:143], v[146:147]
	v_pk_add_f32 v[134:135], v[134:135], v[136:137]
	s_waitcnt vmcnt(0)
; __device__ __forceinline__ unsigned pk2(float lo, float hi) { unsigned r; asm("v_cvt_pk_bf16_f32 %0, %1, %2" : "=v"(r) : "v"(lo), "v"(hi)); return r; }
; __device__ __forceinline__ void norm1_row(const Params& p, const f32x4 (&v)[8], const f32x4 (&sc)[8], const f32x4 (&sh)[8], int row, int lane) {
;     ...
;     for (int j = 0; j < 8; ++j) ss += (v[j].x * v[j].x + v[j].y * v[j].y) + (v[j].z * v[j].z + v[j].w * v[j].w);
;     const float rstd = 1.0f / sqrtf(wave_sum(ss) * (1.0f / DM) + EPS);
; #pragma unroll
;     for (int j = 0; j < 8; ++j) { const int col = 4 * lane + 256 * j;
;         const f32x4 h = v[j] * rstd * sc[j] + sh[j];
;         u32x2 w; w.x = pk2(h.x, h.y); w.y = pk2(h.z, h.w);
;         *(u32x2*)(H + (size_t)row * DM + col) = w; }
	v_mul_f32_e32 v154, v131, v131
	v_mul_f32_e32 v156, v133, v133
	v_pk_add_f32 v[140:141], v[140:141], v[152:153]
	v_pk_add_f32 v[134:135], v[134:135], v[138:139]
	v_mul_f32_e32 v159, v126, v126
	v_mul_f32_e32 v160, v127, v127
	v_mul_f32_e32 v161, v128, v128
	v_mul_f32_e32 v162, v129, v129
	v_pk_fma_f32 v[144:145], v[130:131], v[130:131], v[154:155] op_sel_hi:[1,1,0]
	v_pk_fma_f32 v[148:149], v[132:133], v[132:133], v[156:157] op_sel_hi:[1,1,0]
	v_pk_add_f32 v[140:141], v[140:141], v[140:141] op_sel:[0,1] op_sel_hi:[1,0]
	v_pk_add_f32 v[134:135], v[134:135], v[134:135] op_sel:[0,1] op_sel_hi:[1,0]
	v_mov_b32_e32 v145, v161
	v_mov_b32_e32 v149, v162
	v_mov_b32_e32 v141, v160
	v_mov_b32_e32 v135, v159
	v_pk_add_f32 v[142:143], v[144:145], v[148:149]
	v_pk_add_f32 v[134:135], v[134:135], v[140:141]
	s_nop 0
	v_pk_add_f32 v[134:135], v[134:135], v[142:143]
	s_nop 0
	v_add_f32_e32 v41, v134, v135
	s_nop 1
	v_add_f32_dpp v41, v41, v41 quad_perm:[1,0,3,2] row_mask:0xf bank_mask:0xf
	s_nop 1
	v_add_f32_dpp v41, v41, v41 quad_perm:[2,3,0,1] row_mask:0xf bank_mask:0xf
	s_nop 1
	v_add_f32_dpp v41, v41, v41 row_half_mirror row_mask:0xf bank_mask:0xf
	s_nop 1
	v_add_f32_dpp v41, v41, v41 row_mirror row_mask:0xf bank_mask:0xf
	s_nop 1
	v_add_f32_dpp v41, v41, v41 row_bcast:15 row_mask:0xa bank_mask:0xf
	s_nop 1
	v_add_f32_dpp v41, v41, v41 row_bcast:31 row_mask:0xc bank_mask:0xf
	s_nop 1
	v_readlane_b32 s98, v41, 63
	s_waitcnt lgkmcnt(0)
	s_waitcnt lgkmcnt(0)
	s_waitcnt lgkmcnt(0)
	s_waitcnt lgkmcnt(0)
	s_waitcnt lgkmcnt(0)
	s_waitcnt lgkmcnt(0)
	s_nop 1
	v_mov_b32_e32 v41, s98
	v_fmamk_f32 v41, v41, 0x3a000000, v38
	v_mul_f32_e32 v134, 0x4f800000, v41
	v_cmp_gt_f32_e32 vcc, s17, v41
	s_nop 1
	v_cndmask_b32_e32 v41, v41, v134, vcc
	v_sqrt_f32_e32 v134, v41
	s_nop 0
	v_add_u32_e32 v135, -1, v134
	v_add_u32_e32 v136, 1, v134
	v_fma_f32 v137, -v135, v134, v41
	v_fma_f32 v138, -v136, v134, v41
	v_cmp_ge_f32_e64 s[4:5], 0, v137
	s_nop 1
	v_cndmask_b32_e64 v134, v134, v135, s[4:5]
	v_cmp_lt_f32_e64 s[4:5], 0, v138
	s_nop 1
	v_cndmask_b32_e64 v134, v134, v136, s[4:5]
	v_mul_f32_e32 v135, 0x37800000, v134
	v_cndmask_b32_e32 v134, v134, v135, vcc
	v_cmp_class_f32_e32 vcc, v41, v39
	s_nop 1
	v_cndmask_b32_e32 v41, v134, v41, vcc
	v_div_scale_f32 v134, s[4:5], v41, v41, 1.0
	v_rcp_f32_e32 v136, v134
	v_div_scale_f32 v135, vcc, 1.0, v41, 1.0
	v_fma_f32 v137, -v134, v136, 1.0
	v_fmac_f32_e32 v136, v137, v136
	v_mul_f32_e32 v137, v135, v136
	v_fma_f32 v138, -v134, v137, v135
	v_fmac_f32_e32 v137, v138, v136
	v_fma_f32 v134, -v134, v137, v135
	v_div_fmas_f32 v134, v134, v136, v137
	v_div_fixup_f32 v134, v134, v41, 1.0
	v_pk_mul_f32 v[54:55], v[54:55], v[134:135] op_sel_hi:[1,0]
	v_pk_mul_f32 v[56:57], v[56:57], v[134:135] op_sel_hi:[1,0]
	v_pk_mul_f32 v[58:59], v[58:59], v[134:135] op_sel_hi:[1,0]
	v_pk_mul_f32 v[60:61], v[60:61], v[134:135] op_sel_hi:[1,0]
	v_pk_mul_f32 v[62:63], v[62:63], v[134:135] op_sel_hi:[1,0]
	v_pk_mul_f32 v[64:65], v[64:65], v[134:135] op_sel_hi:[1,0]
	v_pk_mul_f32 v[66:67], v[66:67], v[134:135] op_sel_hi:[1,0]
	v_pk_mul_f32 v[68:69], v[68:69], v[134:135] op_sel_hi:[1,0]
	v_pk_fma_f32 v[46:47], v[46:47], v[54:55], v[50:51]
	v_pk_mul_f32 v[118:119], v[118:119], v[134:135] op_sel_hi:[1,0]
	v_pk_mul_f32 v[120:121], v[120:121], v[134:135] op_sel_hi:[1,0]
	v_pk_mul_f32 v[122:123], v[122:123], v[134:135] op_sel_hi:[1,0]
	v_pk_mul_f32 v[124:125], v[124:125], v[134:135] op_sel_hi:[1,0]
	v_pk_mul_f32 v[130:131], v[130:131], v[134:135] op_sel_hi:[1,0]
	v_pk_mul_f32 v[132:133], v[132:133], v[134:135] op_sel_hi:[1,0]
	v_pk_mul_f32 v[126:127], v[126:127], v[134:135] op_sel_hi:[1,0]
	v_pk_mul_f32 v[128:129], v[128:129], v[134:135] op_sel_hi:[1,0]
	v_pk_fma_f32 v[48:49], v[48:49], v[56:57], v[52:53]
	v_pk_fma_f32 v[26:27], v[80:81], v[60:61], v[26:27]
	v_pk_fma_f32 v[24:25], v[78:79], v[58:59], v[24:25]
	v_pk_fma_f32 v[44:45], v[72:73], v[64:65], v[44:45]
	v_pk_fma_f32 v[42:43], v[70:71], v[62:63], v[42:43]
	v_pk_fma_f32 v[50:51], v[76:77], v[68:69], v[84:85]
	v_pk_fma_f32 v[52:53], v[74:75], v[66:67], v[82:83]
	v_cvt_pk_bf16_f32 v46, v46, v47
	v_cvt_pk_bf16_f32 v47, v48, v49
	v_pk_fma_f32 v[54:55], v[88:89], v[120:121], v[92:93]
	v_pk_fma_f32 v[56:57], v[86:87], v[118:119], v[90:91]
	v_pk_fma_f32 v[58:59], v[96:97], v[124:125], v[100:101]
	v_pk_fma_f32 v[60:61], v[94:95], v[122:123], v[98:99]
	v_pk_fma_f32 v[62:63], v[104:105], v[132:133], v[108:109]
	v_pk_fma_f32 v[64:65], v[102:103], v[130:131], v[106:107]
	v_pk_fma_f32 v[66:67], v[112:113], v[128:129], v[116:117]
	v_pk_fma_f32 v[68:69], v[110:111], v[126:127], v[114:115]
	v_cvt_pk_bf16_f32 v24, v24, v25
	v_cvt_pk_bf16_f32 v25, v26, v27
	v_cvt_pk_bf16_f32 v26, v42, v43
	v_cvt_pk_bf16_f32 v27, v44, v45
	v_cvt_pk_bf16_f32 v42, v52, v53
	v_cvt_pk_bf16_f32 v43, v50, v51
	v_cvt_pk_bf16_f32 v44, v56, v57
	v_cvt_pk_bf16_f32 v45, v54, v55
	v_cvt_pk_bf16_f32 v48, v60, v61
	v_cvt_pk_bf16_f32 v49, v58, v59
	v_cvt_pk_bf16_f32 v50, v64, v65
	v_cvt_pk_bf16_f32 v51, v62, v63
	s_nop 0
	v_cvt_pk_bf16_f32 v52, v68, v69
	v_cvt_pk_bf16_f32 v53, v66, v67
	global_store_dwordx2 v[2:3], v[46:47], off
	global_store_dwordx2 v[2:3], v[24:25], off offset:512
	global_store_dwordx2 v[2:3], v[26:27], off offset:1024
	global_store_dwordx2 v[2:3], v[42:43], off offset:1536
	global_store_dwordx2 v[2:3], v[44:45], off offset:2048
	global_store_dwordx2 v[2:3], v[48:49], off offset:2560
	global_store_dwordx2 v[2:3], v[50:51], off offset:3072
	global_store_dwordx2 v[2:3], v[52:53], off offset:3584
	v_lshl_add_u64 v[2:3], v[2:3], 0, s[10:11]
	s_andn2_b64 exec, exec, s[14:15]
	s_cbranch_execnz .LBB0_173

; __device__ __forceinline__ float bflo(unsigned w) { return __uint_as_float(w << 16); }
; __device__ __forceinline__ float bfhi(unsigned w) { return __uint_as_float(w & 0xffff0000u); }
; __device__ __forceinline__ void mid_row(const Params& p, const f32x4 (&x)[8], f32x4 (&v)[8], const f32x4 (&G1)[8], const f32x4 (&S2)[8], const f32x4 (&sh2)[8], int row, int lane) {
;     bf16_t* H = (bf16_t*)(p.ws + WS_H2);
;     float ss = 0.f;
; #pragma unroll
;     for (int j = 0; j < 8; ++j) ss += (v[j].x * v[j].x + v[j].y * v[j].y) + (v[j].z * v[j].z + v[j].w * v[j].w);
;     const float rstd = 1.0f / sqrtf(wave_sum(ss) * (1.0f / DM) + EPS);
; __device__ __forceinline__ void phase_mid(const Params& p) {
;     ...
;             for (int j = 0; j < 8; ++j) { const int col = 4 * lane + 256 * j; G1[j] = *(const f32x4*)(ar + 2 * DM + col); }
;             if (row + NGW < MPROMPT) { const f32x4* xr = (const f32x4*)(p.in[I_XP] + (size_t)(row + NGW) * DM) + lane; const u32x2* mr = (const u32x2*)(Ob + (size_t)(row + NGW) * DM) + lane;
; #pragma unroll
;                 for (int j = 0; j < 8; ++j) { xn[j] = __builtin_nontemporal_load(xr + 64 * j); mbn[j] = __builtin_nontemporal_load(mr + 64 * j); } }
; #pragma unroll
;             for (int j = 0; j < 8; ++j) { const int col = 4 * lane + 256 * j; S2[j] = *(const f32x4*)(ar + 4 * DM + col); sh2[j] = *(const f32x4*)(ar + 3 * DM + col); }
;             f32x4 v[8];
; #pragma unroll
;             for (int j = 0; j < 8; ++j) v[j] = (f32x4){bflo(mb[j].x), bfhi(mb[j].x), bflo(mb[j].y), bfhi(mb[j].y)};
.LBB0_1112:
	s_or_b64 exec, exec, s[0:1]
	s_waitcnt vmcnt(19)
	v_and_b32_e32 v179, 0xffff0000, v106
	v_and_b32_e32 v181, 0xffff0000, v107
	v_lshlrev_b32_e32 v178, 16, v106
	v_lshlrev_b32_e32 v180, 16, v107
	v_mul_f32_e32 v106, v181, v181
	s_waitcnt vmcnt(18)
	v_and_b32_e32 v187, 0xffff0000, v105
	v_and_b32_e32 v186, 0xffff0000, v104
	s_waitcnt vmcnt(17)
	v_lshlrev_b32_e32 v188, 16, v102
	v_and_b32_e32 v189, 0xffff0000, v102
	v_mul_f32_e32 v102, v179, v179
	s_waitcnt vmcnt(16)
	v_lshlrev_b32_e32 v173, 16, v108
	v_pk_fma_f32 v[106:107], v[180:181], v[180:181], v[106:107] op_sel_hi:[1,1,0]
	v_lshlrev_b32_e32 v183, 16, v105
	v_lshlrev_b32_e32 v182, 16, v104
	v_pk_mul_f32 v[104:105], v[186:187], v[186:187]
	v_lshlrev_b32_e32 v190, 16, v103
	v_and_b32_e32 v191, 0xffff0000, v103
	v_pk_fma_f32 v[102:103], v[178:179], v[178:179], v[102:103] op_sel_hi:[1,1,0]
	v_and_b32_e32 v175, 0xffff0000, v108
	v_lshlrev_b32_e32 v176, 16, v109
	v_and_b32_e32 v177, 0xffff0000, v109
	v_pk_fma_f32 v[104:105], v[182:183], v[182:183], v[104:105]
	v_mov_b32_e32 v172, v102
	v_mov_b32_e32 v108, v106
	v_mov_b32_e32 v109, v173
	s_waitcnt vmcnt(8)
	v_lshlrev_b32_e32 v159, 16, v110
	v_and_b32_e32 v157, 0xffff0000, v110
	v_mul_f32_e32 v110, v175, v175
	v_pk_add_f32 v[102:103], v[102:103], v[106:107]
	v_pk_mul_f32 v[106:107], v[172:173], v[108:109]
	v_pk_add_f32 v[104:105], v[104:105], v[104:105] op_sel:[0,1] op_sel_hi:[1,0]
	v_mov_b32_e32 v103, v107
	v_mov_b32_e32 v105, v110
	v_pk_add_f32 v[102:103], v[102:103], v[104:105]
	v_mul_f32_e32 v104, v189, v189
	v_mul_f32_e32 v106, v191, v191
	v_lshlrev_b32_e32 v154, 16, v111
	v_and_b32_e32 v155, 0xffff0000, v111
	v_mul_f32_e32 v111, v176, v176
	v_mul_f32_e32 v145, v177, v177
	v_pk_fma_f32 v[104:105], v[188:189], v[188:189], v[104:105] op_sel_hi:[1,1,0]
	v_pk_fma_f32 v[106:107], v[190:191], v[190:191], v[106:107] op_sel_hi:[1,1,0]
	v_mov_b32_e32 v105, v111
	v_mov_b32_e32 v107, v145
	v_and_b32_e32 v195, 0xffff0000, v101
	v_and_b32_e32 v194, 0xffff0000, v100
	v_pk_add_f32 v[104:105], v[104:105], v[106:107]
	v_lshlrev_b32_e32 v193, 16, v101
	v_lshlrev_b32_e32 v192, 16, v100
	v_pk_mul_f32 v[100:101], v[194:195], v[194:195]
	v_pk_add_f32 v[102:103], v[102:103], v[104:105]
	v_pk_fma_f32 v[100:101], v[192:193], v[192:193], v[100:101]
	v_and_b32_e32 v199, 0xffff0000, v99
	v_and_b32_e32 v198, 0xffff0000, v98
	v_pk_add_f32 v[100:101], v[100:101], v[100:101] op_sel:[0,1] op_sel_hi:[1,0]
	v_lshlrev_b32_e32 v197, 16, v99
	v_lshlrev_b32_e32 v196, 16, v98
	v_pk_mul_f32 v[98:99], v[198:199], v[198:199]
	v_lshlrev_b32_e32 v200, 16, v96
	v_and_b32_e32 v201, 0xffff0000, v96
	v_lshlrev_b32_e32 v202, 16, v97
	v_and_b32_e32 v203, 0xffff0000, v97
	v_pk_add_f32 v[96:97], v[102:103], v[102:103] op_sel:[0,1] op_sel_hi:[1,0]
	v_pk_fma_f32 v[98:99], v[196:197], v[196:197], v[98:99]
	v_mov_b32_e32 v158, v96
	v_mov_b32_e32 v102, v100
	v_mov_b32_e32 v103, v159
	v_mul_f32_e32 v104, v157, v157
	v_pk_add_f32 v[96:97], v[96:97], v[100:101]
	v_pk_mul_f32 v[100:101], v[158:159], v[102:103]
	v_pk_add_f32 v[98:99], v[98:99], v[98:99] op_sel:[0,1] op_sel_hi:[1,0]
	v_mov_b32_e32 v97, v101
	v_mov_b32_e32 v99, v104
	v_pk_add_f32 v[96:97], v[96:97], v[98:99]
	v_mul_f32_e32 v98, v201, v201
	v_mul_f32_e32 v100, v203, v203
	v_mul_f32_e32 v105, v154, v154
	v_mul_f32_e32 v106, v155, v155
	v_pk_fma_f32 v[98:99], v[200:201], v[200:201], v[98:99] op_sel_hi:[1,1,0]
	v_pk_fma_f32 v[100:101], v[202:203], v[202:203], v[100:101] op_sel_hi:[1,1,0]
	v_mov_b32_e32 v99, v105
	v_mov_b32_e32 v101, v106
	v_pk_add_f32 v[98:99], v[98:99], v[100:101]
	v_lshl_add_u64 v[162:163], v[160:161], 0, s[54:55]
	v_pk_add_f32 v[96:97], v[96:97], v[98:99]
	v_lshl_add_u64 v[160:161], v[160:161], 0, s[56:57]
	v_add_f32_e32 v96, v96, v97
	s_nop 1
	v_add_f32_dpp v96, v96, v96 quad_perm:[1,0,3,2] row_mask:0xf bank_mask:0xf
	s_nop 1
	v_add_f32_dpp v96, v96, v96 quad_perm:[2,3,0,1] row_mask:0xf bank_mask:0xf
	s_nop 1
	v_add_f32_dpp v96, v96, v96 row_half_mirror row_mask:0xf bank_mask:0xf
	s_nop 1
	v_add_f32_dpp v96, v96, v96 row_mirror row_mask:0xf bank_mask:0xf
	s_nop 1
	v_add_f32_dpp v96, v96, v96 row_bcast:15 row_mask:0xa bank_mask:0xf
	s_nop 1
	v_add_f32_dpp v96, v96, v96 row_bcast:31 row_mask:0xc bank_mask:0xf
	s_nop 1
	v_readlane_b32 s98, v96, 63
	v_lshl_add_u64 v[100:101], v[160:161], 0, v[112:113]
	v_lshl_add_u64 v[104:105], v[162:163], 0, v[122:123]
	v_lshl_add_u64 v[108:109], v[160:161], 0, v[122:123]
	v_lshl_add_u64 v[204:205], v[162:163], 0, v[124:125]
	s_waitcnt lgkmcnt(0)
	v_lshl_add_u64 v[206:207], v[160:161], 0, v[124:125]
	v_mov_b32_e32 v174, v173
	s_waitcnt lgkmcnt(0)
	s_waitcnt lgkmcnt(0)
	s_waitcnt lgkmcnt(0)
	s_waitcnt lgkmcnt(0)
	v_lshl_add_u64 v[96:97], v[162:163], 0, v[112:113]
	s_waitcnt lgkmcnt(0)
	s_nop 1
	v_mov_b32_e32 v98, s98
	v_fmamk_f32 v98, v98, 0x3a000000, v170
	v_mul_f32_e32 v99, 0x4f800000, v98
	v_cmp_gt_f32_e32 vcc, s16, v98
	s_nop 1
	v_cndmask_b32_e32 v106, v98, v99, vcc
	v_sqrt_f32_e32 v107, v106
	global_load_dwordx4 v[96:99], v[96:97], off
	s_nop 0
	global_load_dwordx4 v[100:103], v[100:101], off
	v_add_u32_e32 v110, -1, v107
	v_fma_f32 v111, -v110, v107, v106
	v_cmp_ge_f32_e64 s[8:9], 0, v111
	v_add_u32_e32 v111, 1, v107
	s_nop 0
	v_cndmask_b32_e64 v110, v107, v110, s[8:9]
	v_fma_f32 v107, -v111, v107, v106
	v_cmp_lt_f32_e64 s[8:9], 0, v107
	s_nop 1
	v_cndmask_b32_e64 v107, v110, v111, s[8:9]
	v_mul_f32_e32 v110, 0x37800000, v107
	v_cndmask_b32_e32 v107, v107, v110, vcc
	v_cmp_class_f32_e32 vcc, v106, v171
	s_nop 1
	v_cndmask_b32_e32 v112, v107, v106, vcc
	v_div_scale_f32 v123, s[0:1], v112, v112, 1.0
	v_rcp_f32_e32 v145, v123
	global_load_dwordx4 v[104:107], v[104:105], off
	s_nop 0
	global_load_dwordx4 v[108:111], v[108:109], off
	v_fma_f32 v125, -v123, v145, 1.0
	v_fmac_f32_e32 v145, v125, v145
	v_div_scale_f32 v125, vcc, 1.0, v112, 1.0
	v_mul_f32_e32 v156, v125, v145
	v_fma_f32 v158, -v123, v156, v125
	v_fmac_f32_e32 v156, v158, v145
	v_fma_f32 v123, -v123, v156, v125
	v_div_fmas_f32 v123, v123, v145, v156
	v_div_fixup_f32 v112, v123, v112, 1.0
	v_pk_mul_f32 v[178:179], v[112:113], v[178:179] op_sel_hi:[0,1]
	s_waitcnt vmcnt(11)
; __device__ __forceinline__ void mid_row(const Params& p, const f32x4 (&x)[8], f32x4 (&v)[8], const f32x4 (&G1)[8], const f32x4 (&S2)[8], const f32x4 (&sh2)[8], int row, int lane) {
;     ...
;     float ss2 = 0.f;
; #pragma unroll
;     for (int j = 0; j < 8; ++j) { const int col = 4 * lane + 256 * j;
;         v[j] = x[j] + G1[j] * (v[j] * rstd);
;         __builtin_nontemporal_store(v[j], (f32x4*)(p.out + (size_t)row * DM + col));
;         ss2 += (v[j].x * v[j].x + v[j].y * v[j].y) + (v[j].z * v[j].z + v[j].w * v[j].w); }
;     const float rstd2 = 1.0f / sqrtf(wave_sum(ss2) * (1.0f / DM) + EPS);
	v_pk_fma_f32 v[60:61], v[92:93], v[178:179], v[60:61]
	v_mov_b32_e32 v92, v182
	v_mov_b32_e32 v93, v186
	v_pk_mul_f32 v[180:181], v[112:113], v[180:181] op_sel_hi:[0,1]
	v_pk_mul_f32 v[92:93], v[112:113], v[92:93] op_sel_hi:[0,1]
	v_mov_b32_e32 v186, v183
	v_pk_fma_f32 v[62:63], v[94:95], v[180:181], v[62:63]
	v_pk_mul_f32 v[94:95], v[112:113], v[186:187] op_sel_hi:[0,1]
	s_waitcnt vmcnt(10)
	v_pk_fma_f32 v[56:57], v[88:89], v[92:93], v[56:57]
	v_pk_fma_f32 v[58:59], v[90:91], v[94:95], v[58:59]
	v_mov_b32_e32 v90, v61
	v_mov_b32_e32 v91, v57
	v_mov_b32_e32 v88, v60
	v_mov_b32_e32 v89, v56
	v_pk_mul_f32 v[90:91], v[90:91], v[90:91]
	v_mov_b32_e32 v92, v63
	v_mov_b32_e32 v93, v59
	v_pk_fma_f32 v[88:89], v[88:89], v[88:89], v[90:91]
	v_mov_b32_e32 v90, v62
	v_mov_b32_e32 v91, v58
	v_pk_mul_f32 v[92:93], v[92:93], v[92:93]
	v_mov_b32_e32 v156, v159
	v_pk_fma_f32 v[90:91], v[90:91], v[90:91], v[92:93]
	v_pk_mul_f32 v[92:93], v[112:113], v[190:191] op_sel_hi:[0,1]
	v_pk_add_f32 v[88:89], v[88:89], v[90:91]
	v_pk_mul_f32 v[90:91], v[112:113], v[188:189] op_sel_hi:[0,1]
	s_waitcnt vmcnt(9)
	v_pk_fma_f32 v[54:55], v[86:87], v[92:93], v[54:55]
	v_pk_fma_f32 v[52:53], v[84:85], v[90:91], v[52:53]
	v_pk_mul_f32 v[84:85], v[54:55], v[54:55]
	v_pk_mul_f32 v[86:87], v[52:53], v[52:53]
	v_pk_add_f32 v[88:89], v[88:89], v[88:89] op_sel_hi:[0,1]
	v_pk_mov_b32 v[90:91], v[86:87], v[84:85] op_sel:[1,0]
	v_mov_b32_e32 v87, v85
	v_pk_add_f32 v[84:85], v[90:91], v[86:87]
	v_pk_mul_f32 v[86:87], v[112:113], v[174:175] op_sel_hi:[0,1]
	s_waitcnt vmcnt(8)
	v_pk_fma_f32 v[48:49], v[80:81], v[86:87], v[48:49]
	v_pk_mul_f32 v[90:91], v[112:113], v[176:177] op_sel_hi:[0,1]
	v_mul_f32_e32 v80, v48, v48
	v_pk_fma_f32 v[50:51], v[82:83], v[90:91], v[50:51]
	v_pk_fma_f32 v[80:81], v[48:49], v[48:49], v[80:81] op_sel_hi:[1,1,0]
	v_mov_b32_e32 v86, v192
	v_mov_b32_e32 v87, v194
	v_mov_b32_e32 v194, v193
	v_mul_f32_e32 v80, v50, v50
	v_pk_mul_f32 v[86:87], v[112:113], v[86:87] op_sel_hi:[0,1]
	v_pk_mul_f32 v[90:91], v[112:113], v[194:195] op_sel_hi:[0,1]
	v_pk_add_f32 v[84:85], v[84:85], v[84:85] op_sel_hi:[0,1]
	v_pk_fma_f32 v[82:83], v[50:51], v[50:51], v[80:81] op_sel_hi:[1,1,0]
	s_waitcnt vmcnt(7)
	v_pk_fma_f32 v[46:47], v[78:79], v[90:91], v[46:47]
	v_pk_fma_f32 v[44:45], v[76:77], v[86:87], v[44:45]
	v_mul_f32_e32 v84, v46, v46
	v_mul_f32_e32 v80, v44, v44
	v_mul_f32_e32 v82, v45, v45
	v_mul_f32_e32 v88, v47, v47
	v_pk_add_f32 v[76:77], v[80:81], v[82:83]
	v_pk_add_f32 v[78:79], v[84:85], v[88:89]
	v_lshl_add_u64 v[84:85], v[160:161], 0, v[128:129]
	v_pk_add_f32 v[76:77], v[76:77], v[78:79]
	v_mov_b32_e32 v78, v196
	v_mov_b32_e32 v79, v198
	v_mov_b32_e32 v198, v197
	v_pk_mul_f32 v[78:79], v[112:113], v[78:79] op_sel_hi:[0,1]
	v_pk_mul_f32 v[80:81], v[112:113], v[198:199] op_sel_hi:[0,1]
	s_waitcnt vmcnt(6)
	v_pk_fma_f32 v[42:43], v[74:75], v[80:81], v[42:43]
	v_pk_fma_f32 v[40:41], v[72:73], v[78:79], v[40:41]
	v_pk_mul_f32 v[72:73], v[42:43], v[42:43]
	v_pk_mul_f32 v[74:75], v[40:41], v[40:41]
	v_pk_add_f32 v[76:77], v[76:77], v[76:77] op_sel_hi:[0,1]
	v_pk_mov_b32 v[78:79], v[74:75], v[72:73] op_sel:[1,0]
	v_mov_b32_e32 v75, v73
	v_pk_add_f32 v[72:73], v[78:79], v[74:75]
	v_pk_mul_f32 v[74:75], v[112:113], v[200:201] op_sel_hi:[0,1]
	s_waitcnt vmcnt(5)
	v_pk_fma_f32 v[36:37], v[68:69], v[74:75], v[36:37]
	v_pk_mul_f32 v[78:79], v[112:113], v[202:203] op_sel_hi:[0,1]
	v_mul_f32_e32 v68, v36, v36
	v_pk_fma_f32 v[38:39], v[70:71], v[78:79], v[38:39]
	v_pk_fma_f32 v[68:69], v[36:37], v[36:37], v[68:69] op_sel_hi:[1,1,0]
	v_pk_mul_f32 v[74:75], v[112:113], v[156:157] op_sel_hi:[0,1]
	v_mul_f32_e32 v68, v38, v38
	v_pk_mul_f32 v[78:79], v[112:113], v[154:155] op_sel_hi:[0,1]
	v_pk_add_f32 v[72:73], v[72:73], v[72:73] op_sel_hi:[0,1]
	v_pk_fma_f32 v[70:71], v[38:39], v[38:39], v[68:69] op_sel_hi:[1,1,0]
	s_waitcnt vmcnt(4)
	v_pk_fma_f32 v[34:35], v[66:67], v[78:79], v[34:35]
	v_pk_fma_f32 v[32:33], v[64:65], v[74:75], v[32:33]
	v_mul_f32_e32 v72, v34, v34
	v_mul_f32_e32 v68, v32, v32
	v_mul_f32_e32 v70, v33, v33
	v_mul_f32_e32 v76, v35, v35
	v_pk_add_f32 v[64:65], v[68:69], v[70:71]
	v_pk_add_f32 v[66:67], v[72:73], v[76:77]
	v_lshl_add_u64 v[72:73], v[162:163], 0, v[126:127]
	v_pk_add_f32 v[64:65], v[64:65], v[66:67]
	v_lshl_add_u64 v[76:77], v[160:161], 0, v[126:127]
	v_add_f32_e32 v74, v64, v65
	s_nop 1
	v_add_f32_dpp v74, v74, v74 quad_perm:[1,0,3,2] row_mask:0xf bank_mask:0xf
	s_nop 1
	v_add_f32_dpp v74, v74, v74 quad_perm:[2,3,0,1] row_mask:0xf bank_mask:0xf
	s_nop 1
	v_add_f32_dpp v74, v74, v74 row_half_mirror row_mask:0xf bank_mask:0xf
	s_nop 1
	v_add_f32_dpp v74, v74, v74 row_mirror row_mask:0xf bank_mask:0xf
	s_nop 1
	v_add_f32_dpp v74, v74, v74 row_bcast:15 row_mask:0xa bank_mask:0xf
	s_nop 1
	v_add_f32_dpp v74, v74, v74 row_bcast:31 row_mask:0xc bank_mask:0xf
	s_nop 1
	v_readlane_b32 s98, v74, 63
	v_lshl_add_u64 v[80:81], v[162:163], 0, v[128:129]
	v_lshl_add_u64 v[88:89], v[162:163], 0, v[130:131]
	v_lshl_add_u64 v[92:93], v[160:161], 0, v[130:131]
	v_lshl_add_u64 v[154:155], v[162:163], 0, v[132:133]
	s_waitcnt lgkmcnt(0)
	v_lshl_add_u64 v[158:159], v[160:161], 0, v[132:133]
	global_load_dwordx4 v[64:67], v[204:205], off
	global_load_dwordx4 v[68:71], v[206:207], off
	s_nop 0
	global_load_dwordx4 v[72:75], v[72:73], off
	s_nop 0
	global_load_dwordx4 v[76:79], v[76:77], off
	s_waitcnt lgkmcnt(0)
	global_load_dwordx4 v[80:83], v[80:81], off
	s_nop 0
	global_load_dwordx4 v[84:87], v[84:85], off
	s_waitcnt lgkmcnt(0)
; __device__ __forceinline__ unsigned pk2(float lo, float hi) { unsigned r; asm("v_cvt_pk_bf16_f32 %0, %1, %2" : "=v"(r) : "v"(lo), "v"(hi)); return r; }
; __device__ __forceinline__ float bflo(unsigned w) { return __uint_as_float(w << 16); }
; __device__ __forceinline__ float bfhi(unsigned w) { return __uint_as_float(w & 0xffff0000u); }
; __device__ __forceinline__ void mid_row(const Params& p, const f32x4 (&x)[8], f32x4 (&v)[8], const f32x4 (&G1)[8], const f32x4 (&S2)[8], const f32x4 (&sh2)[8], int row, int lane) {
;     ...
;     const float rstd2 = 1.0f / sqrtf(wave_sum(ss2) * (1.0f / DM) + EPS);
; #pragma unroll
;     for (int j = 0; j < 8; ++j) { const int col = 4 * lane + 256 * j;
;         const f32x4 h = v[j] * rstd2 * S2[j] + sh2[j];
;         u32x2 w; w.x = pk2(h.x, h.y); w.y = pk2(h.z, h.w);
;         *(u32x2*)(H + (size_t)row * DM + col) = w; }
; __device__ __forceinline__ void phase_mid(const Params& p) {
;     ...
;             if (row + NGW < MPROMPT) { const f32x4* xr = (const f32x4*)(p.in[I_XP] + (size_t)(row + NGW) * DM) + lane; const u32x2* mr = (const u32x2*)(Ob + (size_t)(row + NGW) * DM) + lane;
; #pragma unroll
;                 for (int j = 0; j < 8; ++j) { xn[j] = __builtin_nontemporal_load(xr + 64 * j); mbn[j] = __builtin_nontemporal_load(mr + 64 * j); } }
; #pragma unroll
;             for (int j = 0; j < 8; ++j) { const int col = 4 * lane + 256 * j; S2[j] = *(const f32x4*)(ar + 4 * DM + col); sh2[j] = *(const f32x4*)(ar + 3 * DM + col); }
;             f32x4 v[8];
; #pragma unroll
;             for (int j = 0; j < 8; ++j) v[j] = (f32x4){bflo(mb[j].x), bfhi(mb[j].x), bflo(mb[j].y), bfhi(mb[j].y)};
;             mid_row(p, x, v, G1, S2, sh2, row, lane);
; #pragma unroll
;             for (int j = 0; j < 8; ++j) { x[j] = xn[j]; mb[j] = mbn[j]; }
	global_load_dwordx4 v[88:91], v[88:89], off
	s_nop 0
	global_load_dwordx4 v[92:95], v[92:93], off
	s_nop 0
	global_load_dwordx4 v[154:157], v[154:155], off
	s_nop 0
	global_load_dwordx4 v[172:175], v[158:159], off
	v_lshl_add_u64 v[158:159], v[162:163], 0, v[134:135]
	v_lshl_add_u64 v[162:163], v[160:161], 0, v[134:135]
	global_load_dwordx4 v[158:161], v[158:159], off
	s_nop 0
	global_load_dwordx4 v[176:179], v[162:163], off
	global_store_dwordx4 v[120:121], v[60:63], off offset:-4096 nt
	global_store_dwordx4 v[120:121], v[56:59], off offset:-3072 nt
	global_store_dwordx4 v[120:121], v[52:55], off offset:-2048 nt
	global_store_dwordx4 v[120:121], v[48:51], off offset:-1024 nt
	global_store_dwordx4 v[120:121], v[44:47], off nt
	global_store_dwordx4 v[120:121], v[40:43], off offset:1024 nt
	global_store_dwordx4 v[120:121], v[36:39], off offset:2048 nt
	global_store_dwordx4 v[120:121], v[32:35], off offset:3072 nt
	v_lshl_add_u64 v[120:121], v[120:121], 0, s[18:19]
	s_waitcnt lgkmcnt(0)
	s_waitcnt lgkmcnt(0)
	s_waitcnt lgkmcnt(0)
	s_nop 1
	v_mov_b32_e32 v112, s98
	v_fmamk_f32 v112, v112, 0x3a000000, v170
	v_mul_f32_e32 v123, 0x4f800000, v112
	v_cmp_gt_f32_e32 vcc, s16, v112
	s_nop 1
	v_cndmask_b32_e32 v112, v112, v123, vcc
	v_sqrt_f32_e32 v123, v112
	s_nop 0
	v_add_u32_e32 v125, -1, v123
	v_fma_f32 v127, -v125, v123, v112
	v_cmp_ge_f32_e64 s[8:9], 0, v127
	v_add_u32_e32 v127, 1, v123
	s_nop 0
	v_cndmask_b32_e64 v125, v123, v125, s[8:9]
	v_fma_f32 v123, -v127, v123, v112
	v_cmp_lt_f32_e64 s[8:9], 0, v123
	s_nop 1
	v_cndmask_b32_e64 v123, v125, v127, s[8:9]
	v_mul_f32_e32 v125, 0x37800000, v123
	v_cndmask_b32_e32 v123, v123, v125, vcc
	v_cmp_class_f32_e32 vcc, v112, v171
	s_nop 1
	v_cndmask_b32_e32 v112, v123, v112, vcc
	v_div_scale_f32 v123, s[0:1], v112, v112, 1.0
	v_rcp_f32_e32 v125, v123
	s_nop 0
	v_fma_f32 v127, -v123, v125, 1.0
	v_fmac_f32_e32 v125, v127, v125
	v_div_scale_f32 v127, vcc, 1.0, v112, 1.0
	v_mul_f32_e32 v129, v127, v125
	v_fma_f32 v131, -v123, v129, v127
	v_fmac_f32_e32 v129, v131, v125
	v_fma_f32 v123, -v123, v129, v127
	v_div_fmas_f32 v123, v123, v125, v129
	v_div_fixup_f32 v112, v123, v112, 1.0
	v_pk_mul_f32 v[60:61], v[60:61], v[112:113] op_sel_hi:[1,0]
	v_pk_mul_f32 v[56:57], v[56:57], v[112:113] op_sel_hi:[1,0]
	v_pk_mul_f32 v[52:53], v[52:53], v[112:113] op_sel_hi:[1,0]
	v_pk_mul_f32 v[48:49], v[48:49], v[112:113] op_sel_hi:[1,0]
	v_pk_mul_f32 v[44:45], v[44:45], v[112:113] op_sel_hi:[1,0]
	v_pk_mul_f32 v[40:41], v[40:41], v[112:113] op_sel_hi:[1,0]
	v_pk_mul_f32 v[36:37], v[36:37], v[112:113] op_sel_hi:[1,0]
	v_pk_mul_f32 v[32:33], v[32:33], v[112:113] op_sel_hi:[1,0]
	v_pk_mul_f32 v[62:63], v[62:63], v[112:113] op_sel_hi:[1,0]
	s_waitcnt vmcnt(22)
	v_pk_fma_f32 v[60:61], v[96:97], v[60:61], v[100:101]
	v_pk_mul_f32 v[58:59], v[58:59], v[112:113] op_sel_hi:[1,0]
	s_waitcnt vmcnt(20)
	v_pk_fma_f32 v[56:57], v[104:105], v[56:57], v[108:109]
	v_pk_mul_f32 v[54:55], v[54:55], v[112:113] op_sel_hi:[1,0]
	s_waitcnt vmcnt(18)
	v_pk_fma_f32 v[52:53], v[64:65], v[52:53], v[68:69]
	v_pk_mul_f32 v[50:51], v[50:51], v[112:113] op_sel_hi:[1,0]
	s_waitcnt vmcnt(16)
	v_pk_fma_f32 v[48:49], v[72:73], v[48:49], v[76:77]
	v_pk_mul_f32 v[46:47], v[46:47], v[112:113] op_sel_hi:[1,0]
	s_waitcnt vmcnt(14)
	v_pk_fma_f32 v[44:45], v[80:81], v[44:45], v[84:85]
	v_pk_mul_f32 v[42:43], v[42:43], v[112:113] op_sel_hi:[1,0]
	s_waitcnt vmcnt(12)
	v_pk_fma_f32 v[40:41], v[88:89], v[40:41], v[92:93]
	v_pk_mul_f32 v[38:39], v[38:39], v[112:113] op_sel_hi:[1,0]
	s_waitcnt vmcnt(10)
	v_pk_fma_f32 v[36:37], v[154:155], v[36:37], v[172:173]
	v_pk_mul_f32 v[34:35], v[34:35], v[112:113] op_sel_hi:[1,0]
	s_waitcnt vmcnt(8)
	v_pk_fma_f32 v[32:33], v[158:159], v[32:33], v[176:177]
	v_pk_fma_f32 v[62:63], v[98:99], v[62:63], v[102:103]
	v_cvt_pk_bf16_f32 v60, v60, v61
	v_pk_fma_f32 v[58:59], v[106:107], v[58:59], v[110:111]
	v_cvt_pk_bf16_f32 v61, v62, v63
	v_cvt_pk_bf16_f32 v56, v56, v57
	v_pk_fma_f32 v[54:55], v[66:67], v[54:55], v[70:71]
	v_cvt_pk_bf16_f32 v57, v58, v59
	v_cvt_pk_bf16_f32 v52, v52, v53
	v_pk_fma_f32 v[50:51], v[74:75], v[50:51], v[78:79]
	v_cvt_pk_bf16_f32 v53, v54, v55
	v_cvt_pk_bf16_f32 v48, v48, v49
	v_pk_fma_f32 v[46:47], v[82:83], v[46:47], v[86:87]
	v_cvt_pk_bf16_f32 v49, v50, v51
	v_cvt_pk_bf16_f32 v44, v44, v45
	v_pk_fma_f32 v[42:43], v[90:91], v[42:43], v[94:95]
	v_cvt_pk_bf16_f32 v45, v46, v47
	v_cvt_pk_bf16_f32 v40, v40, v41
	v_pk_fma_f32 v[38:39], v[156:157], v[38:39], v[174:175]
	v_cvt_pk_bf16_f32 v41, v42, v43
	v_cvt_pk_bf16_f32 v36, v36, v37
	v_pk_fma_f32 v[34:35], v[160:161], v[34:35], v[178:179]
	v_cvt_pk_bf16_f32 v37, v38, v39
	v_cvt_pk_bf16_f32 v32, v32, v33
	global_store_dwordx2 v[118:119], v[60:61], off
	v_cvt_pk_bf16_f32 v33, v34, v35
	global_store_dwordx2 v[118:119], v[56:57], off offset:512
	global_store_dwordx2 v[118:119], v[52:53], off offset:1024
	global_store_dwordx2 v[118:119], v[48:49], off offset:1536
	global_store_dwordx2 v[118:119], v[44:45], off offset:2048
	global_store_dwordx2 v[118:119], v[40:41], off offset:2560
	global_store_dwordx2 v[118:119], v[36:37], off offset:3072
	global_store_dwordx2 v[118:119], v[32:33], off offset:3584
	v_mov_b64_e32 v[62:63], v[2:3]
	v_mov_b64_e32 v[58:59], v[6:7]
	v_mov_b64_e32 v[54:55], v[10:11]
	v_mov_b64_e32 v[50:51], v[14:15]
	v_mov_b64_e32 v[46:47], v[18:19]
	v_mov_b64_e32 v[42:43], v[22:23]
	v_mov_b64_e32 v[38:39], v[26:27]
	v_mov_b64_e32 v[34:35], v[30:31]
	v_lshl_add_u64 v[118:119], v[118:119], 0, s[14:15]
	v_mov_b64_e32 v[106:107], v[136:137]
	v_mov_b64_e32 v[104:105], v[138:139]
	v_mov_b64_e32 v[102:103], v[140:141]
	v_mov_b64_e32 v[108:109], v[142:143]
	v_mov_b64_e32 v[100:101], v[146:147]
	v_mov_b64_e32 v[98:99], v[148:149]
	v_mov_b64_e32 v[96:97], v[150:151]
	v_mov_b64_e32 v[110:111], v[152:153]
	v_mov_b64_e32 v[60:61], v[0:1]
	v_mov_b64_e32 v[56:57], v[4:5]
	v_mov_b64_e32 v[52:53], v[8:9]
	v_mov_b64_e32 v[48:49], v[12:13]
	v_mov_b64_e32 v[44:45], v[16:17]
	v_mov_b64_e32 v[40:41], v[20:21]
	v_mov_b64_e32 v[36:37], v[24:25]
	v_mov_b64_e32 v[32:33], v[28:29]
	s_andn2_b64 exec, exec, s[46:47]
	s_cbranch_execz .LBB0_1115

; __device__ __forceinline__ void mid_row(const Params& p, const f32x4 (&x)[8], f32x4 (&v)[8], const f32x4 (&G1)[8], const f32x4 (&S2)[8], const f32x4 (&sh2)[8], int row, int lane) {
;     bf16_t* H = (bf16_t*)(p.ws + WS_H2);
;     float ss = 0.f;
; #pragma unroll
;     for (int j = 0; j < 8; ++j) ss += (v[j].x * v[j].x + v[j].y * v[j].y) + (v[j].z * v[j].z + v[j].w * v[j].w);
;     const float rstd = 1.0f / sqrtf(wave_sum(ss) * (1.0f / DM) + EPS);
; __device__ __forceinline__ void phase_mid(const Params& p) {
;     ...
;     for (int row = MPROMPT + (gw >> 1); (gw & 1) == 0 && row < MTOK; row += (NGW >> 1)) {
;         const float* ar = ada + (size_t)seq_of_row(row) * NADA;
;         f32x4 v[8]; load_mo_row(v, Ob, Os, row, lane);
;         f32x4 x[8], G1[8], S2[8], sh2[8]; const f32x4* xr = (const f32x4*)xrow_ptr(p, row) + lane;
; #pragma unroll
;         for (int j = 0; j < 8; ++j) { const int col = 4 * lane + 256 * j; x[j] = __builtin_nontemporal_load(xr + 64 * j); G1[j] = *(const f32x4*)(ar + 2 * DM + col); S2[j] = *(const f32x4*)(ar + 4 * DM + col); sh2[j] = *(const f32x4*)(ar + 3 * DM + col); }
.LBB0_1117:
	s_or_b64 exec, exec, s[10:11]
	v_pk_mul_f32 v[58:59], v[28:29], v[28:29]
	v_pk_mul_f32 v[88:89], v[24:25], v[24:25]
	v_pk_mul_f32 v[54:55], v[30:31], v[30:31]
	v_pk_mul_f32 v[56:57], v[26:27], v[26:27]
	v_mov_b32_e32 v90, v58
	v_mov_b32_e32 v91, v88
	v_mov_b32_e32 v88, v59
	v_pk_mul_f32 v[50:51], v[22:23], v[22:23]
	v_pk_mul_f32 v[52:53], v[20:21], v[20:21]
	v_pk_add_f32 v[58:59], v[90:91], v[88:89]
	v_mov_b32_e32 v88, v54
	v_mov_b32_e32 v89, v56
	v_mov_b32_e32 v56, v55
	v_pk_add_f32 v[54:55], v[88:89], v[56:57]
	v_pk_mov_b32 v[56:57], v[52:53], v[50:51] op_sel:[1,0]
	v_mov_b32_e32 v53, v51
	v_pk_add_f32 v[50:51], v[56:57], v[52:53]
	v_pk_add_f32 v[54:55], v[58:59], v[54:55]
	v_pk_add_f32 v[50:51], v[50:51], v[50:51] op_sel_hi:[0,1]
	v_mul_f32_e32 v50, v16, v16
	v_pk_fma_f32 v[52:53], v[16:17], v[16:17], v[50:51] op_sel_hi:[1,1,0]
	v_mul_f32_e32 v50, v18, v18
	v_pk_add_f32 v[54:55], v[54:55], v[54:55] op_sel_hi:[0,1]
	v_pk_fma_f32 v[56:57], v[18:19], v[18:19], v[50:51] op_sel_hi:[1,1,0]
	v_mul_f32_e32 v52, v12, v12
	v_mul_f32_e32 v56, v13, v13
	v_mul_f32_e32 v50, v14, v14
	v_mul_f32_e32 v54, v15, v15
	v_pk_mul_f32 v[46:47], v[10:11], v[10:11]
	v_pk_mul_f32 v[48:49], v[8:9], v[8:9]
	v_pk_add_f32 v[52:53], v[52:53], v[56:57]
	v_pk_add_f32 v[50:51], v[50:51], v[54:55]
	v_lshrrev_b32_e32 v35, 3, v190
	v_pk_add_f32 v[50:51], v[52:53], v[50:51]
	v_pk_mov_b32 v[52:53], v[48:49], v[46:47] op_sel:[1,0]
	v_mov_b32_e32 v49, v47
	v_pk_add_f32 v[46:47], v[52:53], v[48:49]
	v_pk_add_f32 v[50:51], v[50:51], v[50:51] op_sel_hi:[0,1]
	v_pk_add_f32 v[46:47], v[46:47], v[46:47] op_sel_hi:[0,1]
	v_mul_f32_e32 v46, v4, v4
	v_pk_fma_f32 v[48:49], v[4:5], v[4:5], v[46:47] op_sel_hi:[1,1,0]
	v_mul_f32_e32 v46, v6, v6
	v_pk_fma_f32 v[52:53], v[6:7], v[6:7], v[46:47] op_sel_hi:[1,1,0]
	v_mul_f32_e32 v48, v0, v0
	v_mul_f32_e32 v52, v1, v1
	v_mul_f32_e32 v46, v2, v2
	v_mul_f32_e32 v50, v3, v3
	v_pk_add_f32 v[48:49], v[48:49], v[52:53]
	v_pk_add_f32 v[46:47], v[46:47], v[50:51]
	v_ashrrev_i32_e32 v34, 11, v160
	v_pk_add_f32 v[46:47], v[48:49], v[46:47]
	v_add_u32_e32 v35, 4, v35
	v_add_f32_e32 v46, v46, v47
	s_nop 1
	v_add_f32_dpp v46, v46, v46 quad_perm:[1,0,3,2] row_mask:0xf bank_mask:0xf
	s_nop 1
	v_add_f32_dpp v46, v46, v46 quad_perm:[2,3,0,1] row_mask:0xf bank_mask:0xf
	s_nop 1
	v_add_f32_dpp v46, v46, v46 row_half_mirror row_mask:0xf bank_mask:0xf
	s_nop 1
	v_add_f32_dpp v46, v46, v46 row_mirror row_mask:0xf bank_mask:0xf
	s_nop 1
	v_add_f32_dpp v46, v46, v46 row_bcast:15 row_mask:0xa bank_mask:0xf
	s_nop 1
	v_add_f32_dpp v46, v46, v46 row_bcast:31 row_mask:0xc bank_mask:0xf
	s_nop 1
	v_readlane_b32 s98, v46, 63
	v_cndmask_b32_e64 v36, v35, v34, s[8:9]
	v_mov_b64_e32 v[34:35], s[84:85]
	v_mad_i64_i32 v[34:35], s[0:1], v36, s20, v[34:35]
	s_waitcnt lgkmcnt(0)
	v_lshl_add_u64 v[32:33], v[32:33], 0, v[192:193]
	v_lshl_add_u64 v[132:133], v[34:35], 0, s[46:47]
	v_lshl_add_u64 v[80:81], v[34:35], 0, s[48:49]
	v_lshl_add_u64 v[82:83], v[34:35], 0, s[54:55]
	v_mov_b32_e32 v173, v163
	v_mov_b32_e32 v175, v163
	v_lshl_add_u64 v[40:41], v[32:33], 0, v[162:163]
	v_lshl_add_u64 v[32:33], v[132:133], 0, v[172:173]
	v_lshl_add_u64 v[34:35], v[80:81], 0, v[172:173]
	v_lshl_add_u64 v[36:37], v[82:83], 0, v[172:173]
	v_lshl_add_u64 v[42:43], v[132:133], 0, v[174:175]
	v_mov_b32_e32 v177, v163
	global_load_dwordx4 v[68:71], v[32:33], off
	s_nop 0
	global_load_dwordx4 v[32:35], v[34:35], off
	s_nop 0
	global_load_dwordx4 v[72:75], v[40:41], off nt
	global_load_dwordx4 v[60:63], v[40:41], off offset:1024 nt
	s_nop 0
	global_load_dwordx4 v[36:39], v[36:37], off
	s_nop 0
	global_load_dwordx4 v[64:67], v[42:43], off
	v_lshl_add_u64 v[42:43], v[132:133], 0, v[176:177]
	v_lshl_add_u64 v[44:45], v[80:81], 0, v[176:177]
	global_load_dwordx4 v[88:91], v[42:43], off
	global_load_dwordx4 v[52:55], v[44:45], off
	v_lshl_add_u64 v[42:43], v[82:83], 0, v[176:177]
	v_mov_b32_e32 v179, v163
	global_load_dwordx4 v[92:95], v[40:41], off offset:2048 nt
	global_load_dwordx4 v[96:99], v[40:41], off offset:3072 nt
	v_lshl_add_u64 v[44:45], v[132:133], 0, v[178:179]
	global_load_dwordx4 v[56:59], v[42:43], off
	global_load_dwordx4 v[100:103], v[44:45], off
	s_waitcnt lgkmcnt(0)
	v_add_co_u32_e32 v128, vcc, s17, v40
	v_mov_b32_e32 v181, v163
	s_nop 0
	v_addc_co_u32_e32 v129, vcc, 0, v41, vcc
	s_waitcnt lgkmcnt(0)
	v_lshl_add_u64 v[40:41], v[132:133], 0, v[180:181]
	v_lshl_add_u64 v[42:43], v[80:81], 0, v[180:181]
	global_load_dwordx4 v[104:107], v[40:41], off
	global_load_dwordx4 v[44:47], v[42:43], off
	global_load_dwordx4 v[108:111], v[128:129], off nt
	global_load_dwordx4 v[112:115], v[128:129], off offset:1024 nt
	s_waitcnt lgkmcnt(0)
	v_lshl_add_u64 v[40:41], v[82:83], 0, v[180:181]
	v_mov_b32_e32 v183, v163
	v_lshl_add_u64 v[42:43], v[132:133], 0, v[182:183]
	v_mov_b32_e32 v185, v163
	s_waitcnt lgkmcnt(0)
	global_load_dwordx4 v[48:51], v[40:41], off
	global_load_dwordx4 v[116:119], v[42:43], off
	v_lshl_add_u64 v[40:41], v[132:133], 0, v[184:185]
	v_lshl_add_u64 v[42:43], v[80:81], 0, v[184:185]
	v_mov_b32_e32 v187, v163
	s_waitcnt lgkmcnt(0)
; __device__ __forceinline__ void mid_row(const Params& p, const f32x4 (&x)[8], f32x4 (&v)[8], const f32x4 (&G1)[8], const f32x4 (&S2)[8], const f32x4 (&sh2)[8], int row, int lane) {
;     ...
;     const float rstd = 1.0f / sqrtf(wave_sum(ss) * (1.0f / DM) + EPS);
;     float ss2 = 0.f;
; #pragma unroll
;     for (int j = 0; j < 8; ++j) { const int col = 4 * lane + 256 * j;
;         v[j] = x[j] + G1[j] * (v[j] * rstd);
;         __builtin_nontemporal_store(v[j], (f32x4*)(p.out + (size_t)row * DM + col));
;         ss2 += (v[j].x * v[j].x + v[j].y * v[j].y) + (v[j].z * v[j].z + v[j].w * v[j].w); }
	s_nop 1
	v_mov_b32_e32 v120, s98
	v_fmamk_f32 v120, v120, 0x3a000000, v202
	v_mul_f32_e32 v121, 0x4f800000, v120
	v_cmp_gt_f32_e32 vcc, s21, v120
	v_lshl_add_u64 v[132:133], v[132:133], 0, v[186:187]
	v_lshl_add_u64 v[84:85], v[80:81], 0, v[174:175]
	v_cndmask_b32_e32 v134, v120, v121, vcc
	v_sqrt_f32_e32 v135, v134
	global_load_dwordx4 v[120:123], v[40:41], off
	s_nop 0
	global_load_dwordx4 v[40:43], v[42:43], off
	s_nop 0
	global_load_dwordx4 v[124:127], v[128:129], off offset:2048 nt
	s_nop 0
	global_load_dwordx4 v[128:131], v[128:129], off offset:3072 nt
	v_lshl_add_u64 v[86:87], v[82:83], 0, v[174:175]
	v_readlane_b32 s56, v254, 33
	v_add_u32_e32 v136, -1, v135
	v_fma_f32 v137, -v136, v135, v134
	v_cmp_ge_f32_e64 s[8:9], 0, v137
	v_add_u32_e32 v137, 1, v135
	v_readlane_b32 s70, v254, 47
	v_cndmask_b32_e64 v136, v135, v136, s[8:9]
	v_fma_f32 v135, -v137, v135, v134
	v_cmp_lt_f32_e64 s[8:9], 0, v135
	v_readlane_b32 s71, v254, 48
	v_add_u32_e32 v160, s5, v160
	v_cndmask_b32_e64 v135, v136, v137, s[8:9]
	v_mul_f32_e32 v136, 0x37800000, v135
	v_cndmask_b32_e32 v135, v135, v136, vcc
	v_cmp_class_f32_e32 vcc, v134, v203
	v_lshl_add_u64 v[78:79], s[70:71], 0, v[78:79]
	v_add_u32_e32 v188, s5, v188
	v_cndmask_b32_e32 v136, v135, v134, vcc
	global_load_dwordx4 v[132:135], v[132:133], off
	v_div_scale_f32 v137, s[0:1], v136, v136, 1.0
	v_rcp_f32_e32 v138, v137
	v_readlane_b32 s57, v254, 34
	v_readlane_b32 s58, v254, 35
	v_readlane_b32 s59, v254, 36
	v_fma_f32 v139, -v137, v138, 1.0
	v_fmac_f32_e32 v138, v139, v138
	v_div_scale_f32 v139, vcc, 1.0, v136, 1.0
	v_mul_f32_e32 v140, v139, v138
	v_fma_f32 v141, -v137, v140, v139
	v_fmac_f32_e32 v140, v141, v138
	v_fma_f32 v137, -v137, v140, v139
	v_div_fmas_f32 v137, v137, v138, v140
	v_div_fixup_f32 v136, v137, v136, 1.0
	v_pk_mul_f32 v[28:29], v[28:29], v[136:137] op_sel_hi:[1,0]
	v_pk_mul_f32 v[24:25], v[24:25], v[136:137] op_sel_hi:[1,0]
	v_pk_mul_f32 v[30:31], v[30:31], v[136:137] op_sel_hi:[1,0]
	s_waitcnt vmcnt(20)
	v_pk_fma_f32 v[28:29], v[68:69], v[28:29], v[72:73]
	v_pk_mul_f32 v[26:27], v[26:27], v[136:137] op_sel_hi:[1,0]
	s_waitcnt vmcnt(17)
	v_pk_fma_f32 v[24:25], v[64:65], v[24:25], v[60:61]
	v_pk_fma_f32 v[30:31], v[70:71], v[30:31], v[74:75]
	v_pk_fma_f32 v[26:27], v[66:67], v[26:27], v[62:63]
	v_mov_b32_e32 v62, v29
	v_mov_b32_e32 v63, v25
	v_mov_b32_e32 v60, v28
	v_mov_b32_e32 v61, v24
	v_pk_mul_f32 v[62:63], v[62:63], v[62:63]
	v_mov_b32_e32 v64, v31
	v_mov_b32_e32 v65, v27
	v_pk_fma_f32 v[60:61], v[60:61], v[60:61], v[62:63]
	v_mov_b32_e32 v62, v30
	v_mov_b32_e32 v63, v26
	v_pk_mul_f32 v[64:65], v[64:65], v[64:65]
	v_pk_mul_f32 v[20:21], v[20:21], v[136:137] op_sel_hi:[1,0]
	v_pk_fma_f32 v[62:63], v[62:63], v[62:63], v[64:65]
	v_pk_mul_f32 v[22:23], v[22:23], v[136:137] op_sel_hi:[1,0]
	v_pk_add_f32 v[60:61], v[60:61], v[62:63]
	s_waitcnt vmcnt(14)
	v_pk_fma_f32 v[22:23], v[90:91], v[22:23], v[94:95]
	v_pk_fma_f32 v[20:21], v[88:89], v[20:21], v[92:93]
	v_pk_mul_f32 v[16:17], v[16:17], v[136:137] op_sel_hi:[1,0]
	v_pk_add_f32 v[60:61], v[60:61], v[60:61] op_sel_hi:[0,1]
	v_pk_mul_f32 v[62:63], v[22:23], v[22:23]
	v_pk_mul_f32 v[64:65], v[20:21], v[20:21]
	v_pk_mul_f32 v[18:19], v[18:19], v[136:137] op_sel_hi:[1,0]
	s_waitcnt vmcnt(11)
	v_pk_fma_f32 v[16:17], v[100:101], v[16:17], v[96:97]
	v_pk_mov_b32 v[66:67], v[64:65], v[62:63] op_sel:[1,0]
	v_mov_b32_e32 v65, v63
	v_pk_fma_f32 v[18:19], v[102:103], v[18:19], v[98:99]
	v_mul_f32_e32 v60, v16, v16
	v_pk_add_f32 v[62:63], v[66:67], v[64:65]
	v_pk_fma_f32 v[64:65], v[16:17], v[16:17], v[60:61] op_sel_hi:[1,1,0]
	v_mul_f32_e32 v60, v18, v18
	v_pk_mul_f32 v[12:13], v[12:13], v[136:137] op_sel_hi:[1,0]
	v_pk_mul_f32 v[14:15], v[14:15], v[136:137] op_sel_hi:[1,0]
	v_pk_add_f32 v[62:63], v[62:63], v[62:63] op_sel_hi:[0,1]
	v_pk_fma_f32 v[66:67], v[18:19], v[18:19], v[60:61] op_sel_hi:[1,1,0]
	s_waitcnt vmcnt(8)
	v_pk_fma_f32 v[14:15], v[106:107], v[14:15], v[110:111]
	v_pk_fma_f32 v[12:13], v[104:105], v[12:13], v[108:109]
	v_mul_f32_e32 v62, v14, v14
	v_mul_f32_e32 v64, v12, v12
	v_mul_f32_e32 v66, v13, v13
	v_mul_f32_e32 v60, v15, v15
	v_pk_add_f32 v[64:65], v[64:65], v[66:67]
	v_pk_add_f32 v[60:61], v[62:63], v[60:61]
	v_pk_mul_f32 v[8:9], v[8:9], v[136:137] op_sel_hi:[1,0]
	v_pk_mul_f32 v[10:11], v[10:11], v[136:137] op_sel_hi:[1,0]
	v_pk_add_f32 v[60:61], v[64:65], v[60:61]
	s_waitcnt vmcnt(5)
	v_pk_fma_f32 v[10:11], v[118:119], v[10:11], v[114:115]
	v_pk_fma_f32 v[8:9], v[116:117], v[8:9], v[112:113]
	v_pk_mul_f32 v[4:5], v[4:5], v[136:137] op_sel_hi:[1,0]
	v_pk_add_f32 v[60:61], v[60:61], v[60:61] op_sel_hi:[0,1]
	v_pk_mul_f32 v[62:63], v[10:11], v[10:11]
	v_pk_mul_f32 v[64:65], v[8:9], v[8:9]
	v_pk_mul_f32 v[6:7], v[6:7], v[136:137] op_sel_hi:[1,0]
	s_waitcnt vmcnt(2)
	v_pk_fma_f32 v[4:5], v[120:121], v[4:5], v[124:125]
	v_pk_mov_b32 v[66:67], v[64:65], v[62:63] op_sel:[1,0]
	v_mov_b32_e32 v65, v63
	v_pk_fma_f32 v[6:7], v[122:123], v[6:7], v[126:127]
	v_mul_f32_e32 v60, v4, v4
	v_pk_add_f32 v[62:63], v[66:67], v[64:65]
	v_pk_fma_f32 v[64:65], v[4:5], v[4:5], v[60:61] op_sel_hi:[1,1,0]
	v_mul_f32_e32 v60, v6, v6
	v_pk_mul_f32 v[0:1], v[0:1], v[136:137] op_sel_hi:[1,0]
	v_pk_mul_f32 v[2:3], v[2:3], v[136:137] op_sel_hi:[1,0]
	v_pk_add_f32 v[62:63], v[62:63], v[62:63] op_sel_hi:[0,1]
	v_pk_fma_f32 v[66:67], v[6:7], v[6:7], v[60:61] op_sel_hi:[1,1,0]
	s_waitcnt vmcnt(0)
; __device__ __forceinline__ unsigned pk2(float lo, float hi) { unsigned r; asm("v_cvt_pk_bf16_f32 %0, %1, %2" : "=v"(r) : "v"(lo), "v"(hi)); return r; }
; __device__ __forceinline__ void mid_row(const Params& p, const f32x4 (&x)[8], f32x4 (&v)[8], const f32x4 (&G1)[8], const f32x4 (&S2)[8], const f32x4 (&sh2)[8], int row, int lane) {
;     ...
;         __builtin_nontemporal_store(v[j], (f32x4*)(p.out + (size_t)row * DM + col));
;         ss2 += (v[j].x * v[j].x + v[j].y * v[j].y) + (v[j].z * v[j].z + v[j].w * v[j].w); }
;     const float rstd2 = 1.0f / sqrtf(wave_sum(ss2) * (1.0f / DM) + EPS);
; #pragma unroll
;     for (int j = 0; j < 8; ++j) { const int col = 4 * lane + 256 * j;
;         const f32x4 h = v[j] * rstd2 * S2[j] + sh2[j];
;         u32x2 w; w.x = pk2(h.x, h.y); w.y = pk2(h.z, h.w);
;         *(u32x2*)(H + (size_t)row * DM + col) = w; }
	v_pk_fma_f32 v[2:3], v[134:135], v[2:3], v[130:131]
	v_pk_fma_f32 v[0:1], v[132:133], v[0:1], v[128:129]
	v_mul_f32_e32 v62, v2, v2
	v_mul_f32_e32 v64, v0, v0
	v_mul_f32_e32 v66, v1, v1
	v_mul_f32_e32 v60, v3, v3
	v_pk_add_f32 v[64:65], v[64:65], v[66:67]
	v_pk_add_f32 v[60:61], v[62:63], v[60:61]
	v_lshl_add_u64 v[68:69], v[82:83], 0, v[184:185]
	v_pk_add_f32 v[60:61], v[64:65], v[60:61]
	v_lshl_add_u64 v[92:93], v[82:83], 0, v[182:183]
	v_add_f32_e32 v72, v60, v61
	s_nop 1
	v_add_f32_dpp v72, v72, v72 quad_perm:[1,0,3,2] row_mask:0xf bank_mask:0xf
	s_nop 1
	v_add_f32_dpp v72, v72, v72 quad_perm:[2,3,0,1] row_mask:0xf bank_mask:0xf
	s_nop 1
	v_add_f32_dpp v72, v72, v72 row_half_mirror row_mask:0xf bank_mask:0xf
	s_nop 1
	v_add_f32_dpp v72, v72, v72 row_mirror row_mask:0xf bank_mask:0xf
	s_nop 1
	v_add_f32_dpp v72, v72, v72 row_bcast:15 row_mask:0xa bank_mask:0xf
	s_nop 1
	v_add_f32_dpp v72, v72, v72 row_bcast:31 row_mask:0xc bank_mask:0xf
	s_nop 1
	v_readlane_b32 s98, v72, 63
	global_load_dwordx4 v[60:63], v[84:85], off
	global_load_dwordx4 v[64:67], v[86:87], off
	v_lshl_add_u64 v[84:85], v[82:83], 0, v[178:179]
	global_load_dwordx4 v[68:71], v[68:69], off
	v_readlane_b32 s60, v254, 37
	s_waitcnt lgkmcnt(0)
	v_lshl_add_u64 v[72:73], v[80:81], 0, v[178:179]
	global_load_dwordx4 v[72:75], v[72:73], off
	s_nop 0
	global_load_dwordx4 v[84:87], v[84:85], off
	v_readlane_b32 s61, v254, 38
	v_readlane_b32 s62, v254, 39
	s_waitcnt lgkmcnt(0)
	v_lshl_add_u64 v[88:89], v[80:81], 0, v[182:183]
	v_lshl_add_u64 v[80:81], v[80:81], 0, v[186:187]
	global_load_dwordx4 v[88:91], v[88:89], off
	s_nop 0
	global_load_dwordx4 v[92:95], v[92:93], off
	v_readlane_b32 s63, v254, 40
	s_waitcnt lgkmcnt(0)
	v_lshl_add_u64 v[96:97], v[82:83], 0, v[186:187]
	global_load_dwordx4 v[80:83], v[80:81], off
	s_nop 0
	global_load_dwordx4 v[96:99], v[96:97], off
	v_readlane_b32 s64, v254, 41
	v_readlane_b32 s65, v254, 42
	v_readlane_b32 s66, v254, 43
	v_readlane_b32 s67, v254, 44
	s_waitcnt lgkmcnt(0)
	v_lshl_add_u64 v[100:101], v[78:79], 0, v[172:173]
	global_store_dwordx4 v[100:101], v[28:31], off nt
	global_store_dwordx4 v[100:101], v[24:27], off offset:1024 nt
	global_store_dwordx4 v[100:101], v[20:23], off offset:2048 nt
	global_store_dwordx4 v[100:101], v[16:19], off offset:3072 nt
	v_lshl_add_u64 v[100:101], v[78:79], 0, v[180:181]
	s_waitcnt lgkmcnt(0)
	global_store_dwordx4 v[100:101], v[12:15], off nt
	v_readlane_b32 s68, v254, 45
	v_readlane_b32 s69, v254, 46
	s_waitcnt lgkmcnt(0)
	s_nop 1
	v_mov_b32_e32 v100, s98
	v_fmamk_f32 v100, v100, 0x3a000000, v202
	v_mul_f32_e32 v101, 0x4f800000, v100
	v_cmp_gt_f32_e32 vcc, s21, v100
	s_nop 1
	v_cndmask_b32_e32 v102, v100, v101, vcc
	v_sqrt_f32_e32 v103, v102
	v_lshl_add_u64 v[100:101], v[78:79], 0, v[182:183]
	global_store_dwordx4 v[100:101], v[8:11], off nt
	v_lshl_add_u64 v[100:101], v[78:79], 0, v[184:185]
	v_add_u32_e32 v104, -1, v103
	v_fma_f32 v105, -v104, v103, v102
	v_cmp_ge_f32_e64 s[8:9], 0, v105
	v_add_u32_e32 v105, 1, v103
	v_lshl_add_u64 v[78:79], v[78:79], 0, v[186:187]
	v_cndmask_b32_e64 v104, v103, v104, s[8:9]
	v_fma_f32 v103, -v105, v103, v102
	v_cmp_lt_f32_e64 s[8:9], 0, v103
	global_store_dwordx4 v[78:79], v[0:3], off nt
	global_store_dwordx4 v[100:101], v[4:7], off nt
	v_cndmask_b32_e64 v103, v104, v105, s[8:9]
	v_mul_f32_e32 v104, 0x37800000, v103
	v_cndmask_b32_e32 v103, v103, v104, vcc
	v_cmp_class_f32_e32 vcc, v102, v203
	s_nop 1
	v_cndmask_b32_e32 v102, v103, v102, vcc
	v_div_scale_f32 v103, s[0:1], v102, v102, 1.0
	v_rcp_f32_e32 v104, v103
	s_nop 0
	v_fma_f32 v78, -v103, v104, 1.0
	v_fmac_f32_e32 v104, v78, v104
	v_div_scale_f32 v78, vcc, 1.0, v102, 1.0
	v_mul_f32_e32 v79, v78, v104
	v_fma_f32 v100, -v103, v79, v78
	v_fmac_f32_e32 v79, v100, v104
	v_fma_f32 v78, -v103, v79, v78
	v_div_fmas_f32 v78, v78, v104, v79
	v_div_fixup_f32 v78, v78, v102, 1.0
	v_pk_mul_f32 v[28:29], v[28:29], v[78:79] op_sel_hi:[1,0]
	v_pk_mul_f32 v[30:31], v[30:31], v[78:79] op_sel_hi:[1,0]
	v_pk_fma_f32 v[28:29], v[32:33], v[28:29], v[36:37]
	v_pk_fma_f32 v[30:31], v[34:35], v[30:31], v[38:39]
	v_pk_mul_f32 v[24:25], v[24:25], v[78:79] op_sel_hi:[1,0]
	v_pk_mul_f32 v[20:21], v[20:21], v[78:79] op_sel_hi:[1,0]
	v_pk_mul_f32 v[16:17], v[16:17], v[78:79] op_sel_hi:[1,0]
	v_pk_mul_f32 v[12:13], v[12:13], v[78:79] op_sel_hi:[1,0]
	v_pk_mul_f32 v[8:9], v[8:9], v[78:79] op_sel_hi:[1,0]
	v_pk_mul_f32 v[4:5], v[4:5], v[78:79] op_sel_hi:[1,0]
	v_pk_mul_f32 v[0:1], v[0:1], v[78:79] op_sel_hi:[1,0]
	v_cmp_lt_i32_e32 vcc, s35, v160
	v_cvt_pk_bf16_f32 v28, v28, v29
	v_cvt_pk_bf16_f32 v29, v30, v31
	v_lshl_add_u64 v[30:31], v[168:169], 0, v[76:77]
	v_pk_mul_f32 v[26:27], v[26:27], v[78:79] op_sel_hi:[1,0]
	s_waitcnt vmcnt(15)
	v_pk_fma_f32 v[24:25], v[60:61], v[24:25], v[64:65]
	v_pk_mul_f32 v[22:23], v[22:23], v[78:79] op_sel_hi:[1,0]
	v_pk_fma_f32 v[20:21], v[52:53], v[20:21], v[56:57]
	v_pk_mul_f32 v[18:19], v[18:19], v[78:79] op_sel_hi:[1,0]
	s_waitcnt vmcnt(12)
	v_pk_fma_f32 v[16:17], v[72:73], v[16:17], v[84:85]
	v_pk_mul_f32 v[14:15], v[14:15], v[78:79] op_sel_hi:[1,0]
	v_pk_fma_f32 v[12:13], v[44:45], v[12:13], v[48:49]
	v_pk_mul_f32 v[10:11], v[10:11], v[78:79] op_sel_hi:[1,0]
	s_waitcnt vmcnt(10)
	v_pk_fma_f32 v[8:9], v[88:89], v[8:9], v[92:93]
	v_pk_mul_f32 v[6:7], v[6:7], v[78:79] op_sel_hi:[1,0]
	v_pk_fma_f32 v[4:5], v[40:41], v[4:5], v[68:69]
	v_pk_mul_f32 v[2:3], v[2:3], v[78:79] op_sel_hi:[1,0]
	s_waitcnt vmcnt(8)
	v_pk_fma_f32 v[0:1], v[80:81], v[0:1], v[96:97]
	s_or_b64 s[14:15], vcc, s[14:15]
	global_store_dwordx2 v[30:31], v[28:29], off
	v_pk_fma_f32 v[26:27], v[62:63], v[26:27], v[66:67]
	v_cvt_pk_bf16_f32 v24, v24, v25
	v_pk_fma_f32 v[22:23], v[54:55], v[22:23], v[58:59]
	v_cvt_pk_bf16_f32 v25, v26, v27
	global_store_dwordx2 v[30:31], v[24:25], off offset:512
	v_cvt_pk_bf16_f32 v20, v20, v21
	v_cvt_pk_bf16_f32 v21, v22, v23
	global_store_dwordx2 v[30:31], v[20:21], off offset:1024
	v_pk_fma_f32 v[18:19], v[74:75], v[18:19], v[86:87]
	v_cvt_pk_bf16_f32 v16, v16, v17
	v_pk_fma_f32 v[14:15], v[46:47], v[14:15], v[50:51]
	v_cvt_pk_bf16_f32 v17, v18, v19
	global_store_dwordx2 v[30:31], v[16:17], off offset:1536
	v_cvt_pk_bf16_f32 v12, v12, v13
	v_cvt_pk_bf16_f32 v13, v14, v15
	global_store_dwordx2 v[30:31], v[12:13], off offset:2048
	v_pk_fma_f32 v[10:11], v[90:91], v[10:11], v[94:95]
	v_cvt_pk_bf16_f32 v8, v8, v9
	v_pk_fma_f32 v[6:7], v[42:43], v[6:7], v[70:71]
	v_cvt_pk_bf16_f32 v9, v10, v11
	global_store_dwordx2 v[30:31], v[8:9], off offset:2560
	v_cvt_pk_bf16_f32 v4, v4, v5
	v_cvt_pk_bf16_f32 v5, v6, v7
	global_store_dwordx2 v[30:31], v[4:5], off offset:3072
	v_pk_fma_f32 v[2:3], v[82:83], v[2:3], v[98:99]
	v_cvt_pk_bf16_f32 v0, v0, v1
	s_nop 0
	v_cvt_pk_bf16_f32 v1, v2, v3
	global_store_dwordx2 v[30:31], v[0:1], off offset:3584
	s_andn2_b64 exec, exec, s[14:15]
	s_cbranch_execz .LBB0_1140

; __device__ __forceinline__ float bflo(unsigned w) { return __uint_as_float(w << 16); }
; __device__ __forceinline__ float bfhi(unsigned w) { return __uint_as_float(w & 0xffff0000u); }
; __device__ __forceinline__ float wave_sum(float v) {
; #pragma unroll
;     for (int o = 1; o < 64; o <<= 1) v += __shfl_xor(v, o);
;     return v;
; }
; __device__ __forceinline__ void phase_final(const Params& p) {
;     ...
;             f32x4 v[8]; float ss = 0.f;
; #pragma unroll
;             for (int j = 0; j < 8; ++j) { v[j] = (f32x4){bflo(mb[j].x), bfhi(mb[j].x), bflo(mb[j].y), bfhi(mb[j].y)}; ss += (v[j].x * v[j].x + v[j].y * v[j].y) + (v[j].z * v[j].z + v[j].w * v[j].w); }
;             const float rstd = 1.0f / sqrtf(wave_sum(ss) * (1.0f / DM) + EPS);
.LBB0_1444:
	s_or_b64 exec, exec, s[2:3]
	s_waitcnt vmcnt(19)
	v_lshlrev_b32_e32 v159, 16, v148
	v_and_b32_e32 v161, 0xffff0000, v148
	s_waitcnt vmcnt(18)
	v_and_b32_e32 v160, 0xffff0000, v146
	v_lshlrev_b32_e32 v163, 16, v149
	v_and_b32_e32 v149, 0xffff0000, v149
	v_and_b32_e32 v148, 0xffff0000, v147
	v_lshlrev_b32_e32 v158, 16, v146
	v_lshlrev_b32_e32 v162, 16, v147
	v_pk_mul_f32 v[146:147], v[160:161], v[160:161]
	v_pk_mul_f32 v[164:165], v[148:149], v[148:149]
	v_pk_fma_f32 v[146:147], v[158:159], v[158:159], v[146:147]
	v_pk_fma_f32 v[164:165], v[162:163], v[162:163], v[164:165]
	s_waitcnt vmcnt(16)
	v_lshlrev_b32_e32 v168, 16, v140
	v_pk_add_f32 v[146:147], v[146:147], v[164:165]
	v_lshlrev_b32_e32 v165, 16, v145
	v_lshlrev_b32_e32 v164, 16, v144
	v_and_b32_e32 v145, 0xffff0000, v145
	v_and_b32_e32 v144, 0xffff0000, v144
	v_pk_add_f32 v[146:147], v[146:147], v[146:147] op_sel_hi:[0,1]
	v_pk_mul_f32 v[166:167], v[144:145], v[144:145]
	v_and_b32_e32 v169, 0xffff0000, v140
	v_lshlrev_b32_e32 v140, 16, v141
	s_waitcnt vmcnt(11)
	v_lshlrev_b32_e32 v170, 16, v142
	v_pk_fma_f32 v[166:167], v[164:165], v[164:165], v[166:167]
	v_mul_f32_e32 v171, v168, v168
	v_mul_f32_e32 v173, v169, v169
	v_and_b32_e32 v141, 0xffff0000, v141
	v_mul_f32_e32 v146, v140, v140
	v_mov_b32_e32 v172, v170
	v_pk_add_f32 v[166:167], v[166:167], v[166:167] op_sel_hi:[0,1]
	v_pk_fma_f32 v[174:175], v[140:141], v[140:141], v[146:147] op_sel_hi:[1,1,0]
	v_and_b32_e32 v105, 0xffff0000, v142
	v_lshlrev_b32_e32 v142, 16, v143
	v_and_b32_e32 v143, 0xffff0000, v143
	v_pk_add_f32 v[172:173], v[170:171], v[172:173]
	v_mul_f32_e32 v174, v105, v105
	v_mul_f32_e32 v166, v142, v142
	v_mul_f32_e32 v146, v143, v143
	v_mul_f32_e32 v176, v170, v170
	v_mov_b32_e32 v177, v173
	v_pk_add_f32 v[172:173], v[176:177], v[174:175]
	v_pk_add_f32 v[146:147], v[166:167], v[146:147]
	s_waitcnt vmcnt(10)
	v_lshlrev_b32_e32 v167, 16, v139
	v_pk_add_f32 v[146:147], v[172:173], v[146:147]
	v_lshlrev_b32_e32 v166, 16, v138
	v_and_b32_e32 v139, 0xffff0000, v139
	v_and_b32_e32 v138, 0xffff0000, v138
	v_pk_add_f32 v[146:147], v[146:147], v[146:147] op_sel_hi:[0,1]
	v_pk_mul_f32 v[172:173], v[138:139], v[138:139]
	s_waitcnt vmcnt(9)
	v_lshlrev_b32_e32 v174, 16, v136
	v_and_b32_e32 v175, 0xffff0000, v136
	v_lshlrev_b32_e32 v136, 16, v137
	s_waitcnt vmcnt(8)
	v_lshlrev_b32_e32 v176, 16, v134
	v_pk_fma_f32 v[172:173], v[166:167], v[166:167], v[172:173]
	v_mul_f32_e32 v177, v174, v174
	v_mul_f32_e32 v179, v175, v175
	v_and_b32_e32 v137, 0xffff0000, v137
	v_mul_f32_e32 v146, v136, v136
	v_mov_b32_e32 v178, v176
	v_pk_add_f32 v[172:173], v[172:173], v[172:173] op_sel_hi:[0,1]
	v_pk_fma_f32 v[180:181], v[136:137], v[136:137], v[146:147] op_sel_hi:[1,1,0]
	v_and_b32_e32 v107, 0xffff0000, v134
	v_lshlrev_b32_e32 v134, 16, v135
	v_and_b32_e32 v135, 0xffff0000, v135
	v_pk_add_f32 v[178:179], v[176:177], v[178:179]
	v_mul_f32_e32 v180, v107, v107
	v_mul_f32_e32 v172, v134, v134
	v_mul_f32_e32 v146, v135, v135
	v_mul_f32_e32 v182, v176, v176
	v_mov_b32_e32 v183, v179
	v_pk_add_f32 v[178:179], v[182:183], v[180:181]
	v_pk_add_f32 v[146:147], v[172:173], v[146:147]
	v_mov_b32_e32 v172, v159
	v_pk_add_f32 v[146:147], v[178:179], v[146:147]
	v_mov_b32_e32 v173, v161
	v_add_f32_e32 v109, v146, v147
	s_nop 1
	v_add_f32_dpp v109, v109, v109 quad_perm:[1,0,3,2] row_mask:0xf bank_mask:0xf
	s_nop 1
	v_add_f32_dpp v109, v109, v109 quad_perm:[2,3,0,1] row_mask:0xf bank_mask:0xf
	s_nop 1
	v_add_f32_dpp v109, v109, v109 row_half_mirror row_mask:0xf bank_mask:0xf
	s_nop 1
	v_add_f32_dpp v109, v109, v109 row_mirror row_mask:0xf bank_mask:0xf
	s_nop 1
	v_add_f32_dpp v109, v109, v109 row_bcast:15 row_mask:0xa bank_mask:0xf
	s_nop 1
	v_add_f32_dpp v109, v109, v109 row_bcast:31 row_mask:0xc bank_mask:0xf
	s_nop 1
	v_readlane_b32 s98, v109, 63
	v_mov_b32_e32 v178, v163
	v_mov_b32_e32 v179, v149
	v_mov_b32_e32 v159, v160
	v_mov_b32_e32 v163, v148
	s_waitcnt lgkmcnt(0)
	v_mov_b32_e32 v171, v105
	v_mov_b32_e32 v177, v107
	s_and_b64 s[0:1], exec, s[0:1]
	s_or_b64 s[12:13], s[0:1], s[12:13]
	s_waitcnt lgkmcnt(0)
	v_lshl_add_u64 v[100:101], v[100:101], 0, s[8:9]
	v_lshl_add_u64 v[102:103], v[102:103], 0, s[10:11]
	v_mov_b64_e32 v[148:149], v[124:125]
	s_waitcnt lgkmcnt(0)
	s_waitcnt lgkmcnt(0)
	s_waitcnt lgkmcnt(0)
	s_waitcnt lgkmcnt(0)
; __device__ __forceinline__ void phase_final(const Params& p) {
;     ...
;             const float rstd = 1.0f / sqrtf(wave_sum(ss) * (1.0f / DM) + EPS);
; #pragma unroll
;             for (int j = 0; j < 8; ++j) { const int col = 4 * lane + 256 * j;
;                 __builtin_nontemporal_store(x[j] + gt2[j] * (v[j] * rstd), (f32x4*)(p.out + (size_t)row * DM + col)); }
; #pragma unroll
;             for (int j = 0; j < 8; ++j) { x[j] = xn[j]; mb[j] = mbn[j]; }
	s_nop 1
	v_mov_b32_e32 v109, s98
	v_fmamk_f32 v109, v109, 0x3a000000, v156
	v_mul_f32_e32 v111, 0x4f800000, v109
	v_cmp_gt_f32_e32 vcc, s19, v109
	s_nop 1
	v_cndmask_b32_e32 v109, v109, v111, vcc
	v_sqrt_f32_e32 v111, v109
	s_nop 0
	v_add_u32_e32 v113, -1, v111
	v_fma_f32 v115, -v113, v111, v109
	v_cmp_ge_f32_e64 s[2:3], 0, v115
	v_add_u32_e32 v115, 1, v111
	s_nop 0
	v_cndmask_b32_e64 v113, v111, v113, s[2:3]
	v_fma_f32 v111, -v115, v111, v109
	v_cmp_lt_f32_e64 s[2:3], 0, v111
	s_nop 1
	v_cndmask_b32_e64 v111, v113, v115, s[2:3]
	v_mul_f32_e32 v113, 0x37800000, v111
	v_cndmask_b32_e32 v111, v111, v113, vcc
	v_cmp_class_f32_e32 vcc, v109, v157
	s_nop 1
	v_cndmask_b32_e32 v109, v111, v109, vcc
	v_div_scale_f32 v111, s[2:3], v109, v109, 1.0
	v_rcp_f32_e32 v113, v111
	s_nop 0
	v_fma_f32 v115, -v111, v113, 1.0
	v_fmac_f32_e32 v113, v115, v113
	v_div_scale_f32 v115, vcc, 1.0, v109, 1.0
	v_mul_f32_e32 v117, v115, v113
	v_fma_f32 v146, -v111, v117, v115
	v_fmac_f32_e32 v117, v146, v113
	v_fma_f32 v111, -v111, v117, v115
	v_div_fmas_f32 v111, v111, v113, v117
	v_div_fixup_f32 v146, v111, v109, 1.0
	v_pk_mul_f32 v[172:173], v[172:173], v[146:147] op_sel_hi:[1,0]
	v_pk_mul_f32 v[178:179], v[178:179], v[146:147] op_sel_hi:[1,0]
	s_waitcnt vmcnt(7)
	v_pk_fma_f32 v[60:61], v[92:93], v[172:173], v[60:61]
	v_pk_fma_f32 v[62:63], v[94:95], v[178:179], v[62:63]
	v_lshl_add_u64 v[92:93], v[98:99], 0, v[214:215]
	global_store_dwordx4 v[92:93], v[60:63], off nt
	v_lshl_add_u64 v[98:99], v[98:99], 0, s[10:11]
	s_nop 0
	v_pk_mul_f32 v[60:61], v[158:159], v[146:147] op_sel_hi:[1,0]
	v_pk_mul_f32 v[62:63], v[162:163], v[146:147] op_sel_hi:[1,0]
	s_waitcnt vmcnt(7)
	v_pk_fma_f32 v[40:41], v[88:89], v[60:61], v[40:41]
	v_pk_fma_f32 v[42:43], v[90:91], v[62:63], v[42:43]
	global_store_dwordx4 v[92:93], v[40:43], off offset:1024 nt
	v_mov_b64_e32 v[62:63], v[22:23]
	v_mov_b64_e32 v[60:61], v[20:21]
	v_mov_b32_e32 v40, v164
	v_mov_b32_e32 v41, v144
	v_mov_b32_e32 v144, v165
	v_pk_mul_f32 v[40:41], v[146:147], v[40:41] op_sel_hi:[0,1]
	v_pk_mul_f32 v[42:43], v[146:147], v[144:145] op_sel_hi:[0,1]
	s_waitcnt vmcnt(7)
	v_pk_fma_f32 v[26:27], v[86:87], v[42:43], v[26:27]
	v_pk_fma_f32 v[24:25], v[84:85], v[40:41], v[24:25]
	global_store_dwordx4 v[92:93], v[24:27], off offset:2048 nt
	v_mov_b64_e32 v[42:43], v[30:31]
	v_mov_b64_e32 v[144:145], v[120:121]
	v_pk_mul_f32 v[24:25], v[168:169], v[146:147] op_sel_hi:[1,0]
	v_pk_mul_f32 v[26:27], v[140:141], v[146:147] op_sel_hi:[1,0]
	s_waitcnt vmcnt(7)
	v_pk_fma_f32 v[16:17], v[80:81], v[24:25], v[16:17]
	v_pk_fma_f32 v[18:19], v[82:83], v[26:27], v[18:19]
	global_store_dwordx4 v[92:93], v[16:19], off offset:3072 nt
	v_mov_b64_e32 v[24:25], v[32:33]
	v_mov_b64_e32 v[140:141], v[118:119]
	v_pk_mul_f32 v[16:17], v[170:171], v[146:147] op_sel_hi:[1,0]
	v_pk_mul_f32 v[18:19], v[142:143], v[146:147] op_sel_hi:[1,0]
	s_waitcnt vmcnt(7)
	v_pk_fma_f32 v[12:13], v[76:77], v[16:17], v[12:13]
	v_add_co_u32_e32 v16, vcc, s16, v92
	v_pk_fma_f32 v[14:15], v[78:79], v[18:19], v[14:15]
	s_nop 0
	v_addc_co_u32_e32 v17, vcc, 0, v93, vcc
	global_store_dwordx4 v[16:17], v[12:15], off nt
	v_mov_b64_e32 v[142:143], v[132:133]
	v_mov_b64_e32 v[40:41], v[28:29]
	v_mov_b32_e32 v12, v166
	v_mov_b32_e32 v13, v138
	v_mov_b32_e32 v138, v167
	v_pk_mul_f32 v[12:13], v[146:147], v[12:13] op_sel_hi:[0,1]
	v_pk_mul_f32 v[14:15], v[146:147], v[138:139] op_sel_hi:[0,1]
	s_waitcnt vmcnt(7)
	v_pk_fma_f32 v[10:11], v[74:75], v[14:15], v[10:11]
	v_pk_fma_f32 v[8:9], v[72:73], v[12:13], v[8:9]
	global_store_dwordx4 v[16:17], v[8:11], off offset:1024 nt
	v_mov_b64_e32 v[12:13], v[44:45]
	v_mov_b64_e32 v[138:139], v[130:131]
	v_pk_mul_f32 v[8:9], v[174:175], v[146:147] op_sel_hi:[1,0]
	v_pk_mul_f32 v[10:11], v[136:137], v[146:147] op_sel_hi:[1,0]
	s_waitcnt vmcnt(7)
	v_pk_fma_f32 v[4:5], v[68:69], v[8:9], v[4:5]
	v_pk_fma_f32 v[6:7], v[70:71], v[10:11], v[6:7]
	global_store_dwordx4 v[16:17], v[4:7], off offset:2048 nt
	v_mov_b64_e32 v[8:9], v[48:49]
	v_mov_b64_e32 v[136:137], v[128:129]
	v_pk_mul_f32 v[4:5], v[176:177], v[146:147] op_sel_hi:[1,0]
	v_pk_mul_f32 v[6:7], v[134:135], v[146:147] op_sel_hi:[1,0]
	s_waitcnt vmcnt(7)
	v_pk_fma_f32 v[0:1], v[64:65], v[4:5], v[0:1]
	v_pk_fma_f32 v[2:3], v[66:67], v[6:7], v[2:3]
	global_store_dwordx4 v[16:17], v[0:3], off offset:3072 nt
	v_mov_b64_e32 v[16:17], v[36:37]
	v_mov_b64_e32 v[4:5], v[52:53]
	v_mov_b64_e32 v[0:1], v[56:57]
	v_mov_b64_e32 v[134:135], v[126:127]
	v_mov_b64_e32 v[146:147], v[122:123]
	v_mov_b64_e32 v[26:27], v[34:35]
	v_mov_b64_e32 v[18:19], v[38:39]
	v_mov_b64_e32 v[14:15], v[46:47]
	v_mov_b64_e32 v[10:11], v[50:51]
	v_mov_b64_e32 v[6:7], v[54:55]
	v_mov_b64_e32 v[2:3], v[58:59]
	s_andn2_b64 exec, exec, s[12:13]
	s_cbranch_execz .LBB0_1447

; __device__ __forceinline__ float wave_sum(float v) {
; #pragma unroll
;     for (int o = 1; o < 64; o <<= 1) v += __shfl_xor(v, o);
;     return v;
; __device__ __forceinline__ void phase_final(const Params& p) {
;     ...
;     for (int row = MPROMPT + (gw >> 1); (gw & 1) == 0 && row < MTOK; row += (NGW >> 1)) {
;         f32x4 v[8]; float ss = 0.f;
;         load_mo_row(v, Ob, Os, row, lane);
; #pragma unroll
;         for (int j = 0; j < 8; ++j) ss += (v[j].x * v[j].x + v[j].y * v[j].y) + (v[j].z * v[j].z + v[j].w * v[j].w);
;         const float rstd = 1.0f / sqrtf(wave_sum(ss) * (1.0f / DM) + EPS);
;         const float* ar = ada + (size_t)seq_of_row(row) * NADA;
; #pragma unroll
;         for (int j = 0; j < 8; ++j) { const int col = 4 * lane + 256 * j;
;             const f32x4 gt2 = *(const f32x4*)(ar + 5 * DM + col);
;             float* o = p.out + (size_t)row * DM + col; const f32x4 x1 = *(const f32x4*)o;
;             *(f32x4*)o = x1 + gt2 * (v[j] * rstd); }
;     }
.LBB0_1449:
	s_or_b64 exec, exec, s[2:3]
	v_pk_mul_f32 v[44:45], v[28:29], v[28:29]
	v_pk_mul_f32 v[46:47], v[24:25], v[24:25]
	v_pk_mul_f32 v[40:41], v[30:31], v[30:31]
	v_pk_mul_f32 v[42:43], v[26:27], v[26:27]
	v_mov_b32_e32 v48, v44
	v_mov_b32_e32 v49, v46
	v_mov_b32_e32 v46, v45
	v_pk_mul_f32 v[36:37], v[22:23], v[22:23]
	v_pk_mul_f32 v[38:39], v[20:21], v[20:21]
	v_pk_add_f32 v[44:45], v[48:49], v[46:47]
	v_mov_b32_e32 v46, v40
	v_mov_b32_e32 v47, v42
	v_mov_b32_e32 v42, v41
	v_pk_add_f32 v[40:41], v[46:47], v[42:43]
	v_pk_mov_b32 v[42:43], v[38:39], v[36:37] op_sel:[1,0]
	v_mov_b32_e32 v39, v37
	v_pk_add_f32 v[36:37], v[42:43], v[38:39]
	v_pk_add_f32 v[40:41], v[44:45], v[40:41]
	v_pk_add_f32 v[36:37], v[36:37], v[36:37] op_sel_hi:[0,1]
	v_mul_f32_e32 v36, v16, v16
	v_pk_fma_f32 v[38:39], v[16:17], v[16:17], v[36:37] op_sel_hi:[1,1,0]
	v_mul_f32_e32 v36, v18, v18
	v_pk_add_f32 v[40:41], v[40:41], v[40:41] op_sel_hi:[0,1]
	v_pk_fma_f32 v[42:43], v[18:19], v[18:19], v[36:37] op_sel_hi:[1,1,0]
	v_mul_f32_e32 v38, v12, v12
	v_mul_f32_e32 v42, v13, v13
	v_mul_f32_e32 v36, v14, v14
	v_mul_f32_e32 v40, v15, v15
	v_pk_add_f32 v[38:39], v[38:39], v[42:43]
	v_pk_add_f32 v[36:37], v[36:37], v[40:41]
	v_pk_mul_f32 v[32:33], v[10:11], v[10:11]
	v_pk_mul_f32 v[34:35], v[8:9], v[8:9]
	v_pk_add_f32 v[36:37], v[38:39], v[36:37]
	v_readlane_b32 s36, v254, 33
	v_pk_add_f32 v[40:41], v[36:37], v[36:37] op_sel_hi:[0,1]
	v_pk_mov_b32 v[36:37], v[34:35], v[32:33] op_sel:[1,0]
	v_mov_b32_e32 v35, v33
	v_pk_add_f32 v[32:33], v[36:37], v[34:35]
	v_readlane_b32 s50, v254, 47
	v_pk_add_f32 v[42:43], v[32:33], v[32:33] op_sel_hi:[0,1]
	v_mul_f32_e32 v32, v4, v4
	v_pk_fma_f32 v[32:33], v[4:5], v[4:5], v[32:33] op_sel_hi:[1,1,0]
	v_readlane_b32 s51, v254, 48
	v_mul_f32_e32 v32, v6, v6
	v_pk_fma_f32 v[34:35], v[6:7], v[6:7], v[32:33] op_sel_hi:[1,1,0]
	v_mul_f32_e32 v32, v0, v0
	v_mul_f32_e32 v34, v1, v1
	v_pk_add_f32 v[44:45], v[32:33], v[34:35]
	v_lshrrev_b32_e32 v33, 3, v182
	v_ashrrev_i32_e32 v32, 11, v160
	v_add_u32_e32 v33, 4, v33
	v_cndmask_b32_e64 v34, v33, v32, s[0:1]
	v_mov_b64_e32 v[32:33], s[84:85]
	v_mad_i64_i32 v[32:33], s[0:1], v34, s18, v[32:33]
	v_lshl_add_u64 v[46:47], v[32:33], 0, s[8:9]
	v_lshlrev_b64 v[32:33], 13, v[160:161]
	v_lshl_add_u64 v[48:49], s[50:51], 0, v[32:33]
	v_lshl_add_u64 v[32:33], v[46:47], 0, v[214:215]
	v_lshl_add_u64 v[50:51], v[48:49], 0, v[214:215]
	global_load_dwordx4 v[32:35], v[32:33], off
	v_mul_f32_e32 v42, v2, v2
	global_load_dwordx4 v[36:39], v[50:51], off
	v_mul_f32_e32 v40, v3, v3
	v_pk_add_f32 v[40:41], v[42:43], v[40:41]
	v_mov_b32_e32 v169, v215
	v_pk_add_f32 v[40:41], v[44:45], v[40:41]
	v_mov_b32_e32 v171, v215
	v_add_f32_e32 v40, v40, v41
	s_nop 1
	v_add_f32_dpp v40, v40, v40 quad_perm:[1,0,3,2] row_mask:0xf bank_mask:0xf
	s_nop 1
	v_add_f32_dpp v40, v40, v40 quad_perm:[2,3,0,1] row_mask:0xf bank_mask:0xf
	s_nop 1
	v_add_f32_dpp v40, v40, v40 row_half_mirror row_mask:0xf bank_mask:0xf
	s_nop 1
	v_add_f32_dpp v40, v40, v40 row_mirror row_mask:0xf bank_mask:0xf
	s_nop 1
	v_add_f32_dpp v40, v40, v40 row_bcast:15 row_mask:0xa bank_mask:0xf
	s_nop 1
	v_add_f32_dpp v40, v40, v40 row_bcast:31 row_mask:0xc bank_mask:0xf
	s_nop 1
	v_readlane_b32 s98, v40, 63
	v_mov_b32_e32 v173, v215
	v_mov_b32_e32 v175, v215
	v_mov_b32_e32 v177, v215
	v_mov_b32_e32 v179, v215
	s_waitcnt lgkmcnt(0)
	v_mov_b32_e32 v181, v215
	v_add_u32_e32 v160, s15, v160
	v_add_u32_e32 v216, s15, v216
	v_readlane_b32 s37, v254, 34
	s_waitcnt lgkmcnt(0)
	v_readlane_b32 s38, v254, 35
	v_readlane_b32 s39, v254, 36
	v_readlane_b32 s40, v254, 37
	v_readlane_b32 s41, v254, 38
	s_waitcnt lgkmcnt(0)
	v_readlane_b32 s42, v254, 39
	v_readlane_b32 s43, v254, 40
	v_readlane_b32 s44, v254, 41
	v_readlane_b32 s45, v254, 42
	s_waitcnt lgkmcnt(0)
	v_readlane_b32 s46, v254, 43
	v_readlane_b32 s47, v254, 44
	v_readlane_b32 s48, v254, 45
	v_readlane_b32 s49, v254, 46
	s_waitcnt lgkmcnt(0)
	s_waitcnt lgkmcnt(0)
; __device__ __forceinline__ void phase_final(const Params& p) {
;     ...
;         const float rstd = 1.0f / sqrtf(wave_sum(ss) * (1.0f / DM) + EPS);
;         const float* ar = ada + (size_t)seq_of_row(row) * NADA;
; #pragma unroll
;         for (int j = 0; j < 8; ++j) { const int col = 4 * lane + 256 * j;
;             const f32x4 gt2 = *(const f32x4*)(ar + 5 * DM + col);
;             float* o = p.out + (size_t)row * DM + col; const f32x4 x1 = *(const f32x4*)o;
;             *(f32x4*)o = x1 + gt2 * (v[j] * rstd); }
	s_nop 1
	v_mov_b32_e32 v40, s98
	v_fmamk_f32 v40, v40, 0x3a000000, v192
	v_mul_f32_e32 v41, 0x4f800000, v40
	v_cmp_gt_f32_e32 vcc, s17, v40
	s_nop 1
	v_cndmask_b32_e32 v40, v40, v41, vcc
	v_sqrt_f32_e32 v41, v40
	s_nop 0
	v_add_u32_e32 v42, -1, v41
	v_fma_f32 v43, -v42, v41, v40
	v_cmp_ge_f32_e64 s[0:1], 0, v43
	v_add_u32_e32 v43, 1, v41
	s_nop 0
	v_cndmask_b32_e64 v42, v41, v42, s[0:1]
	v_fma_f32 v41, -v43, v41, v40
	v_cmp_lt_f32_e64 s[0:1], 0, v41
	s_nop 1
	v_cndmask_b32_e64 v41, v42, v43, s[0:1]
	v_mul_f32_e32 v42, 0x37800000, v41
	v_cndmask_b32_e32 v41, v41, v42, vcc
	v_cmp_class_f32_e32 vcc, v40, v193
	s_nop 1
	v_cndmask_b32_e32 v40, v41, v40, vcc
	v_div_scale_f32 v41, s[0:1], v40, v40, 1.0
	v_rcp_f32_e32 v42, v41
	s_nop 0
	v_fma_f32 v43, -v41, v42, 1.0
	v_fmac_f32_e32 v42, v43, v42
	v_div_scale_f32 v43, vcc, 1.0, v40, 1.0
	v_mul_f32_e32 v44, v43, v42
	v_fma_f32 v45, -v41, v44, v43
	v_fmac_f32_e32 v44, v45, v42
	v_fma_f32 v41, -v41, v44, v43
	v_div_fmas_f32 v41, v41, v42, v44
	v_div_fixup_f32 v40, v41, v40, 1.0
	v_pk_mul_f32 v[42:43], v[28:29], v[40:41] op_sel_hi:[1,0]
	v_pk_mul_f32 v[44:45], v[30:31], v[40:41] op_sel_hi:[1,0]
	global_load_dwordx4 v[28:31], v[50:51], off offset:1024
	s_waitcnt vmcnt(1)
	v_pk_fma_f32 v[34:35], v[34:35], v[44:45], v[38:39]
	v_pk_fma_f32 v[32:33], v[32:33], v[42:43], v[36:37]
	global_store_dwordx4 v[50:51], v[32:35], off
	v_pk_mul_f32 v[26:27], v[26:27], v[40:41] op_sel_hi:[1,0]
	v_pk_mul_f32 v[24:25], v[24:25], v[40:41] op_sel_hi:[1,0]
	v_lshl_add_u64 v[32:33], v[46:47], 0, v[168:169]
	global_load_dwordx4 v[32:35], v[32:33], off
	v_lshl_add_u64 v[42:43], v[46:47], 0, v[170:171]
	global_load_dwordx4 v[36:39], v[50:51], off offset:2048
	v_pk_mul_f32 v[22:23], v[22:23], v[40:41] op_sel_hi:[1,0]
	v_pk_mul_f32 v[20:21], v[20:21], v[40:41] op_sel_hi:[1,0]
	v_pk_mul_f32 v[18:19], v[18:19], v[40:41] op_sel_hi:[1,0]
	v_pk_mul_f32 v[16:17], v[16:17], v[40:41] op_sel_hi:[1,0]
	v_pk_mul_f32 v[14:15], v[14:15], v[40:41] op_sel_hi:[1,0]
	v_pk_mul_f32 v[12:13], v[12:13], v[40:41] op_sel_hi:[1,0]
	v_pk_mul_f32 v[10:11], v[10:11], v[40:41] op_sel_hi:[1,0]
	v_pk_mul_f32 v[8:9], v[8:9], v[40:41] op_sel_hi:[1,0]
	v_pk_mul_f32 v[6:7], v[6:7], v[40:41] op_sel_hi:[1,0]
	v_pk_mul_f32 v[4:5], v[4:5], v[40:41] op_sel_hi:[1,0]
	v_cmp_lt_i32_e32 vcc, s19, v160
	v_pk_mul_f32 v[2:3], v[2:3], v[40:41] op_sel_hi:[1,0]
	v_pk_mul_f32 v[0:1], v[0:1], v[40:41] op_sel_hi:[1,0]
	s_or_b64 s[4:5], vcc, s[4:5]
	s_waitcnt vmcnt(1)
	v_pk_fma_f32 v[24:25], v[32:33], v[24:25], v[28:29]
	v_pk_fma_f32 v[26:27], v[34:35], v[26:27], v[30:31]
	global_store_dwordx4 v[50:51], v[24:27], off offset:1024
	global_load_dwordx4 v[24:27], v[42:43], off
	v_lshl_add_u64 v[32:33], v[46:47], 0, v[172:173]
	global_load_dwordx4 v[28:31], v[50:51], off offset:3072
	v_lshl_add_u64 v[34:35], v[46:47], 0, v[174:175]
	s_waitcnt vmcnt(1)
	v_pk_fma_f32 v[20:21], v[24:25], v[20:21], v[36:37]
	v_pk_fma_f32 v[22:23], v[26:27], v[22:23], v[38:39]
	global_store_dwordx4 v[50:51], v[20:23], off offset:2048
	global_load_dwordx4 v[20:23], v[32:33], off
	v_lshl_add_u64 v[32:33], v[48:49], 0, v[174:175]
	global_load_dwordx4 v[24:27], v[32:33], off
	s_waitcnt vmcnt(1)
	v_pk_fma_f32 v[16:17], v[20:21], v[16:17], v[28:29]
	v_pk_fma_f32 v[18:19], v[22:23], v[18:19], v[30:31]
	global_store_dwordx4 v[50:51], v[16:19], off offset:3072
	global_load_dwordx4 v[16:19], v[34:35], off
	v_lshl_add_u64 v[28:29], v[48:49], 0, v[176:177]
	v_lshl_add_u64 v[30:31], v[46:47], 0, v[176:177]
	global_load_dwordx4 v[20:23], v[28:29], off
	s_waitcnt vmcnt(1)
	v_pk_fma_f32 v[12:13], v[16:17], v[12:13], v[24:25]
	v_pk_fma_f32 v[14:15], v[18:19], v[14:15], v[26:27]
	global_store_dwordx4 v[32:33], v[12:15], off
	global_load_dwordx4 v[12:15], v[30:31], off
	v_lshl_add_u64 v[24:25], v[48:49], 0, v[178:179]
	v_lshl_add_u64 v[26:27], v[46:47], 0, v[178:179]
	global_load_dwordx4 v[16:19], v[24:25], off
	s_waitcnt vmcnt(1)
	v_pk_fma_f32 v[8:9], v[12:13], v[8:9], v[20:21]
	v_pk_fma_f32 v[10:11], v[14:15], v[10:11], v[22:23]
	global_store_dwordx4 v[28:29], v[8:11], off
	global_load_dwordx4 v[8:11], v[26:27], off
	v_lshl_add_u64 v[20:21], v[48:49], 0, v[180:181]
	v_lshl_add_u64 v[22:23], v[46:47], 0, v[180:181]
	global_load_dwordx4 v[12:15], v[20:21], off
	s_waitcnt vmcnt(1)
	v_pk_fma_f32 v[4:5], v[4:5], v[8:9], v[16:17]
	v_pk_fma_f32 v[6:7], v[6:7], v[10:11], v[18:19]
	global_store_dwordx4 v[24:25], v[4:7], off
	global_load_dwordx4 v[4:7], v[22:23], off
	s_waitcnt vmcnt(0)
	v_pk_fma_f32 v[0:1], v[0:1], v[4:5], v[12:13]
	v_pk_fma_f32 v[2:3], v[2:3], v[6:7], v[14:15]
	global_store_dwordx4 v[20:21], v[0:3], off
	s_andn2_b64 exec, exec, s[4:5]
	s_cbranch_execz .LBB0_1472
